# XCD-local barrier before the final phase (final items remapped), DPP adds for the first four levels of the epi_resid row-statistics reduction, hmat2 row loads issued together
# speedup vs baseline: 1.0081x; 1.0081x over previous
.LBB0_1820:
	v_lshl_add_u64 v[18:19], v[0:1], 0, s[18:19]
	s_waitcnt lgkmcnt(0)
	global_load_dwordx4 v[26:29], v[18:19], off
	v_add_co_u32_e32 v200, vcc, 0x8000, v18
	s_nop 1
	v_addc_co_u32_e32 v201, vcc, 0, v19, vcc
	global_load_dwordx4 v[208:211], v[200:201], off
	v_add_co_u32_e32 v200, vcc, 0x10000, v18
	s_nop 1
	v_addc_co_u32_e32 v201, vcc, 0, v19, vcc
	global_load_dwordx4 v[212:215], v[200:201], off
	v_add_co_u32_e32 v200, vcc, 0x18000, v18
	s_nop 1
	v_addc_co_u32_e32 v201, vcc, 0, v19, vcc
	global_load_dwordx4 v[216:219], v[200:201], off
	ds_read_b128 v[30:33], v25
	s_waitcnt vmcnt(3) lgkmcnt(0)
	v_pk_fma_f32 v[30:31], v[26:27], s[16:17], v[30:31] op_sel_hi:[1,0,1]
	v_pk_fma_f32 v[32:33], v[28:29], s[16:17], v[32:33] op_sel_hi:[1,0,1]
	v_pk_mul_f32 v[26:27], v[30:31], v[30:31]
	v_add_f32_e32 v34, v30, v31
	v_pk_mul_f32 v[28:29], v[32:33], v[32:33]
	v_add_f32_e32 v26, v26, v27
	v_add_f32_e32 v34, v32, v34
	v_add_f32_e32 v26, v28, v26
	v_add_f32_e32 v27, v33, v34
	v_add_f32_e32 v26, v29, v26
	v_lshl_add_u64 v[34:35], v[14:15], 0, s[18:19]
	v_add_co_u32_e32 v34, vcc, s56, v34
	s_nop 1
	v_add_f32_dpp v27, v27, v27 quad_perm:[1,0,3,2] row_mask:0xf bank_mask:0xf
	v_add_f32_dpp v26, v26, v26 quad_perm:[1,0,3,2] row_mask:0xf bank_mask:0xf
	v_addc_co_u32_e32 v35, vcc, 0, v35, vcc
	global_store_dwordx4 v[34:35], v[30:33], off offset:3584
	s_nop 1
	v_add_f32_dpp v27, v27, v27 quad_perm:[2,3,0,1] row_mask:0xf bank_mask:0xf
	v_add_f32_dpp v26, v26, v26 quad_perm:[2,3,0,1] row_mask:0xf bank_mask:0xf
	s_nop 1
	v_add_f32_dpp v27, v27, v27 row_half_mirror row_mask:0xf bank_mask:0xf
	v_add_f32_dpp v28, v26, v26 row_half_mirror row_mask:0xf bank_mask:0xf
	s_nop 1
	v_add_f32_dpp v26, v27, v27 row_mirror row_mask:0xf bank_mask:0xf
	v_add_f32_dpp v27, v28, v28 row_mirror row_mask:0xf bank_mask:0xf
	ds_bpermute_b32 v28, v24, v26
	ds_bpermute_b32 v29, v24, v27
	s_and_saveexec_b64 s[22:23], s[0:1]
	s_cbranch_execz .LBB0_1822
	s_waitcnt lgkmcnt(0)
	v_add_f32_e32 v29, v27, v29
	v_add_f32_e32 v28, v26, v28
	v_lshl_add_u64 v[26:27], s[20:21], 0, v[16:17]
	v_add_co_u32_e32 v26, vcc, 0x3c000, v26
	s_nop 1
	v_addc_co_u32_e32 v27, vcc, 0, v27, vcc
	v_mov_b32_e32 v92, v26
	v_mov_b32_e32 v93, v27
	v_and_b32_e32 v90, 0x3ff, v26
	v_add_u32_e32 v90, 68608, v90
	ds_write2_b32 v90, v28, v29 offset1:1
.LBB0_1822:
	s_or_b64 exec, exec, s[22:23]
	v_add_co_u32_e32 v26, vcc, 0x8000, v18
	ds_read_b128 v[30:33], v25 offset:4224
	s_nop 0
	v_addc_co_u32_e32 v27, vcc, 0, v19, vcc
	s_waitcnt lgkmcnt(1)
	s_waitcnt vmcnt(3)
	v_mov_b64_e32 v[26:27], v[208:209]
	v_mov_b64_e32 v[28:29], v[210:211]
	s_waitcnt lgkmcnt(0)
	v_pk_fma_f32 v[30:31], v[26:27], s[16:17], v[30:31] op_sel_hi:[1,0,1]
	v_pk_fma_f32 v[32:33], v[28:29], s[16:17], v[32:33] op_sel_hi:[1,0,1]
	v_pk_mul_f32 v[26:27], v[30:31], v[30:31]
	v_add_f32_e32 v34, v30, v31
	v_pk_mul_f32 v[28:29], v[32:33], v[32:33]
	v_add_f32_e32 v26, v26, v27
	v_add_f32_e32 v34, v32, v34
	v_add_f32_e32 v26, v28, v26
	v_add_f32_e32 v27, v33, v34
	v_add_f32_e32 v26, v29, v26
	v_lshl_add_u64 v[34:35], v[12:13], 0, s[18:19]
	v_add_co_u32_e32 v34, vcc, s56, v34
	s_nop 1
	v_add_f32_dpp v27, v27, v27 quad_perm:[1,0,3,2] row_mask:0xf bank_mask:0xf
	v_add_f32_dpp v26, v26, v26 quad_perm:[1,0,3,2] row_mask:0xf bank_mask:0xf
	v_addc_co_u32_e32 v35, vcc, 0, v35, vcc
	global_store_dwordx4 v[34:35], v[30:33], off offset:3584
	s_nop 1
	v_add_f32_dpp v27, v27, v27 quad_perm:[2,3,0,1] row_mask:0xf bank_mask:0xf
	v_add_f32_dpp v26, v26, v26 quad_perm:[2,3,0,1] row_mask:0xf bank_mask:0xf
	s_nop 1
	v_add_f32_dpp v27, v27, v27 row_half_mirror row_mask:0xf bank_mask:0xf
	v_add_f32_dpp v28, v26, v26 row_half_mirror row_mask:0xf bank_mask:0xf
	s_nop 1
	v_add_f32_dpp v26, v27, v27 row_mirror row_mask:0xf bank_mask:0xf
	v_add_f32_dpp v27, v28, v28 row_mirror row_mask:0xf bank_mask:0xf
	ds_bpermute_b32 v28, v24, v26
	ds_bpermute_b32 v29, v24, v27
	s_and_saveexec_b64 s[22:23], s[0:1]
	s_cbranch_execz .LBB0_1824
	s_waitcnt lgkmcnt(0)
	v_add_f32_e32 v29, v27, v29
	v_add_f32_e32 v28, v26, v28
	v_lshl_add_u64 v[26:27], s[20:21], 0, v[10:11]
	v_add_co_u32_e32 v26, vcc, 0x3c000, v26
	s_nop 1
	v_addc_co_u32_e32 v27, vcc, 0, v27, vcc
	v_mov_b32_e32 v92, v26
	v_mov_b32_e32 v93, v27
	v_and_b32_e32 v90, 0x3ff, v26
	v_add_u32_e32 v90, 68608, v90
	ds_write2_b32 v90, v28, v29 offset1:1
.LBB0_1824:
	s_or_b64 exec, exec, s[22:23]
	v_add_co_u32_e32 v26, vcc, 0x10000, v18
	ds_read_b128 v[30:33], v25 offset:8448
	s_nop 0
	v_addc_co_u32_e32 v27, vcc, 0, v19, vcc
	s_waitcnt lgkmcnt(1)
	s_waitcnt vmcnt(3)
	v_mov_b64_e32 v[26:27], v[212:213]
	v_mov_b64_e32 v[28:29], v[214:215]
	s_waitcnt lgkmcnt(0)
	v_pk_fma_f32 v[30:31], v[26:27], s[16:17], v[30:31] op_sel_hi:[1,0,1]
	v_pk_fma_f32 v[32:33], v[28:29], s[16:17], v[32:33] op_sel_hi:[1,0,1]
	v_pk_mul_f32 v[26:27], v[30:31], v[30:31]
	v_add_f32_e32 v34, v30, v31
	v_pk_mul_f32 v[28:29], v[32:33], v[32:33]
	v_add_f32_e32 v26, v26, v27
	v_add_f32_e32 v34, v32, v34
	v_add_f32_e32 v26, v28, v26
	v_add_f32_e32 v27, v33, v34
	v_add_f32_e32 v26, v29, v26
	v_lshl_add_u64 v[34:35], v[8:9], 0, s[18:19]
	v_add_co_u32_e32 v34, vcc, s56, v34
	s_nop 1
	v_add_f32_dpp v27, v27, v27 quad_perm:[1,0,3,2] row_mask:0xf bank_mask:0xf
	v_add_f32_dpp v26, v26, v26 quad_perm:[1,0,3,2] row_mask:0xf bank_mask:0xf
	v_addc_co_u32_e32 v35, vcc, 0, v35, vcc
	global_store_dwordx4 v[34:35], v[30:33], off offset:3584
	s_nop 1
	v_add_f32_dpp v27, v27, v27 quad_perm:[2,3,0,1] row_mask:0xf bank_mask:0xf
	v_add_f32_dpp v26, v26, v26 quad_perm:[2,3,0,1] row_mask:0xf bank_mask:0xf
	s_nop 1
	v_add_f32_dpp v27, v27, v27 row_half_mirror row_mask:0xf bank_mask:0xf
	v_add_f32_dpp v28, v26, v26 row_half_mirror row_mask:0xf bank_mask:0xf
	s_nop 1
	v_add_f32_dpp v26, v27, v27 row_mirror row_mask:0xf bank_mask:0xf
	v_add_f32_dpp v27, v28, v28 row_mirror row_mask:0xf bank_mask:0xf
	ds_bpermute_b32 v28, v24, v26
	ds_bpermute_b32 v29, v24, v27
	s_and_saveexec_b64 s[22:23], s[0:1]
	s_cbranch_execz .LBB0_1826
	s_waitcnt lgkmcnt(0)
	v_add_f32_e32 v29, v27, v29
	v_add_f32_e32 v28, v26, v28
	v_lshl_add_u64 v[26:27], s[20:21], 0, v[6:7]
	v_add_co_u32_e32 v26, vcc, 0x3c000, v26
	s_nop 1
	v_addc_co_u32_e32 v27, vcc, 0, v27, vcc
	v_mov_b32_e32 v92, v26
	v_mov_b32_e32 v93, v27
	v_and_b32_e32 v90, 0x3ff, v26
	v_add_u32_e32 v90, 68608, v90
	ds_write2_b32 v90, v28, v29 offset1:1
.LBB0_1826:
	s_or_b64 exec, exec, s[22:23]
	v_add_co_u32_e32 v18, vcc, 0x18000, v18
	ds_read_b128 v[30:33], v25 offset:12672
	s_nop 0
	v_addc_co_u32_e32 v19, vcc, 0, v19, vcc
	s_waitcnt lgkmcnt(1)
	s_waitcnt vmcnt(3)
	v_mov_b64_e32 v[26:27], v[216:217]
	v_mov_b64_e32 v[28:29], v[218:219]
	s_waitcnt lgkmcnt(0)
	v_pk_fma_f32 v[30:31], v[26:27], s[16:17], v[30:31] op_sel_hi:[1,0,1]
	v_pk_fma_f32 v[32:33], v[28:29], s[16:17], v[32:33] op_sel_hi:[1,0,1]
	v_pk_mul_f32 v[18:19], v[30:31], v[30:31]
	v_add_f32_e32 v28, v30, v31
	v_pk_mul_f32 v[26:27], v[32:33], v[32:33]
	v_add_f32_e32 v18, v18, v19
	v_add_f32_e32 v28, v32, v28
	v_add_f32_e32 v18, v26, v18
	v_add_f32_e32 v19, v33, v28
	v_add_f32_e32 v18, v27, v18
	v_lshl_add_u64 v[28:29], v[4:5], 0, s[18:19]
	v_add_co_u32_e32 v28, vcc, s56, v28
	s_nop 1
	v_add_f32_dpp v19, v19, v19 quad_perm:[1,0,3,2] row_mask:0xf bank_mask:0xf
	v_add_f32_dpp v18, v18, v18 quad_perm:[1,0,3,2] row_mask:0xf bank_mask:0xf
	v_addc_co_u32_e32 v29, vcc, 0, v29, vcc
	global_store_dwordx4 v[28:29], v[30:33], off offset:3584
	s_nop 1
	v_add_f32_dpp v19, v19, v19 quad_perm:[2,3,0,1] row_mask:0xf bank_mask:0xf
	v_add_f32_dpp v18, v18, v18 quad_perm:[2,3,0,1] row_mask:0xf bank_mask:0xf
	s_nop 1
	v_add_f32_dpp v19, v19, v19 row_half_mirror row_mask:0xf bank_mask:0xf
	v_add_f32_dpp v26, v18, v18 row_half_mirror row_mask:0xf bank_mask:0xf
	s_nop 1
	v_add_f32_dpp v18, v19, v19 row_mirror row_mask:0xf bank_mask:0xf
	v_add_f32_dpp v19, v26, v26 row_mirror row_mask:0xf bank_mask:0xf
	ds_bpermute_b32 v26, v24, v18
	ds_bpermute_b32 v27, v24, v19
	s_and_saveexec_b64 s[22:23], s[0:1]
	s_cbranch_execz .LBB0_1819
	s_waitcnt lgkmcnt(0)
	v_add_f32_e32 v27, v19, v27
	v_add_f32_e32 v26, v18, v26
	v_lshl_add_u64 v[18:19], s[20:21], 0, v[2:3]
	v_add_co_u32_e32 v18, vcc, 0x3c000, v18
	s_nop 1
	v_addc_co_u32_e32 v19, vcc, 0, v19, vcc
	v_mov_b32_e32 v92, v18
	v_mov_b32_e32 v93, v19
	v_and_b32_e32 v90, 0x3ff, v18
	v_add_u32_e32 v90, 68608, v90
	ds_write2_b32 v90, v26, v27 offset1:1
	s_branch .LBB0_1819

.LBB0_1881:
	s_add_i32 s5, s6, 0xffffeff9
	s_lshr_b32 s5, s5, 10
	s_mulk_i32 s5, 0x1800
	s_add_i32 s12, s6, -7
	s_addk_i32 s5, 0x1800
	v_mov_b32_e32 v0, v234
	s_cmpk_gt_i32 s20, 0x1ff
	s_cselect_b32 s8, s5, 0
	v_lshlrev_b32_e32 v2, 2, v0
	v_ashrrev_i32_e32 v3, 31, v2
	s_lshl_b64 s[22:23], s[8:9], 2
	v_lshlrev_b64 v[0:1], 2, v[2:3]
	s_add_u32 s22, s30, s22
	v_lshl_add_u64 v[4:5], s[36:37], 0, v[0:1]
	s_addc_u32 s23, s31, s23
	v_lshl_add_u64 v[10:11], s[38:39], 0, v[0:1]
	global_load_dwordx4 v[6:9], v[4:5], off
	global_load_dwordx4 v[14:17], v[10:11], off
	s_ashr_i32 s13, s12, 31
	v_lshl_add_u64 v[4:5], s[22:23], 0, v[0:1]
	s_lshl_b64 s[22:23], s[12:13], 12
	v_add_co_u32_e32 v10, vcc, s18, v4
	s_add_u32 s22, s11, s22
	s_nop 0
	v_addc_co_u32_e32 v11, vcc, 0, v5, vcc
	v_add_co_u32_e32 v4, vcc, s19, v4
	s_addc_u32 s23, s14, s23
	s_add_i32 s24, s4, -14
	v_addc_co_u32_e32 v5, vcc, 0, v5, vcc
	s_ashr_i32 s25, s24, 31
	global_load_dwordx4 v[18:21], v[10:11], off
	global_load_dwordx4 v[22:25], v[4:5], off
	v_lshl_add_u64 v[4:5], s[22:23], 0, v[0:1]
	s_lshl_b64 s[22:23], s[24:25], 2
	s_add_u32 s22, s2, s22
	s_addc_u32 s23, s3, s23
	global_load_dwordx2 v[30:31], v12, s[22:23]
	s_waitcnt lgkmcnt(0)
	global_load_dwordx4 v[26:29], v[4:5], off
	s_add_i32 s96, s4, -12
	s_ashr_i32 s97, s96, 31
	s_lshl_b64 s[96:97], s[96:97], 2
	s_add_u32 s96, s2, s96
	s_addc_u32 s97, s3, s97
	global_load_dwordx2 v[36:37], v12, s[96:97]
	s_add_i32 s96, s6, -6
	s_ashr_i32 s97, s96, 31
	s_lshl_b64 s[96:97], s[96:97], 12
	s_add_u32 s96, s11, s96
	s_addc_u32 s97, s14, s97
	v_lshl_add_u64 v[50:51], s[96:97], 0, v[0:1]
	global_load_dwordx4 v[52:55], v[50:51], off
	s_add_i32 s96, s4, -10
	s_ashr_i32 s97, s96, 31
	s_lshl_b64 s[96:97], s[96:97], 2
	s_add_u32 s96, s2, s96
	s_addc_u32 s97, s3, s97
	global_load_dwordx2 v[38:39], v12, s[96:97]
	s_add_i32 s96, s6, -5
	s_ashr_i32 s97, s96, 31
	s_lshl_b64 s[96:97], s[96:97], 12
	s_add_u32 s96, s11, s96
	s_addc_u32 s97, s14, s97
	v_lshl_add_u64 v[50:51], s[96:97], 0, v[0:1]
	global_load_dwordx4 v[56:59], v[50:51], off
	s_add_i32 s96, s4, -8
	s_ashr_i32 s97, s96, 31
	s_lshl_b64 s[96:97], s[96:97], 2
	s_add_u32 s96, s2, s96
	s_addc_u32 s97, s3, s97
	global_load_dwordx2 v[40:41], v12, s[96:97]
	s_add_i32 s96, s6, -4
	s_ashr_i32 s97, s96, 31
	s_lshl_b64 s[96:97], s[96:97], 12
	s_add_u32 s96, s11, s96
	s_addc_u32 s97, s14, s97
	v_lshl_add_u64 v[50:51], s[96:97], 0, v[0:1]
	global_load_dwordx4 v[60:63], v[50:51], off
	s_add_i32 s96, s4, -6
	s_ashr_i32 s97, s96, 31
	s_lshl_b64 s[96:97], s[96:97], 2
	s_add_u32 s96, s2, s96
	s_addc_u32 s97, s3, s97
	global_load_dwordx2 v[42:43], v12, s[96:97]
	s_add_i32 s96, s6, -3
	s_ashr_i32 s97, s96, 31
	s_lshl_b64 s[96:97], s[96:97], 12
	s_add_u32 s96, s11, s96
	s_addc_u32 s97, s14, s97
	v_lshl_add_u64 v[50:51], s[96:97], 0, v[0:1]
	global_load_dwordx4 v[64:67], v[50:51], off
	s_add_i32 s96, s4, -4
	s_ashr_i32 s97, s96, 31
	s_lshl_b64 s[96:97], s[96:97], 2
	s_add_u32 s96, s2, s96
	s_addc_u32 s97, s3, s97
	global_load_dwordx2 v[44:45], v12, s[96:97]
	s_add_i32 s96, s6, -2
	s_ashr_i32 s97, s96, 31
	s_lshl_b64 s[96:97], s[96:97], 12
	s_add_u32 s96, s11, s96
	s_addc_u32 s97, s14, s97
	v_lshl_add_u64 v[50:51], s[96:97], 0, v[0:1]
	global_load_dwordx4 v[68:71], v[50:51], off
	s_add_i32 s96, s4, -2
	s_ashr_i32 s97, s96, 31
	s_lshl_b64 s[96:97], s[96:97], 2
	s_add_u32 s96, s2, s96
	s_addc_u32 s97, s3, s97
	global_load_dwordx2 v[46:47], v12, s[96:97]
	s_add_i32 s96, s6, -1
	s_ashr_i32 s97, s96, 31
	s_lshl_b64 s[96:97], s[96:97], 12
	s_add_u32 s96, s11, s96
	s_addc_u32 s97, s14, s97
	v_lshl_add_u64 v[50:51], s[96:97], 0, v[0:1]
	global_load_dwordx4 v[72:75], v[50:51], off
	s_add_i32 s96, s4, 0
	s_ashr_i32 s97, s96, 31
	s_lshl_b64 s[96:97], s[96:97], 2
	s_add_u32 s96, s2, s96
	s_addc_u32 s97, s3, s97
	global_load_dwordx2 v[48:49], v12, s[96:97]
	s_add_i32 s96, s6, 0
	s_ashr_i32 s97, s96, 31
	s_lshl_b64 s[96:97], s[96:97], 12
	s_add_u32 s96, s11, s96
	s_addc_u32 s97, s14, s97
	v_lshl_add_u64 v[50:51], s[96:97], 0, v[0:1]
	global_load_dwordx4 v[76:79], v[50:51], off
	s_add_i32 s22, s6, -6
	v_lshl_add_u64 v[2:3], v[2:3], 1, s[0:1]
	s_lshl_b64 s[12:13], s[12:13], 11
	s_ashr_i32 s23, s22, 31
	s_waitcnt vmcnt(26)
	v_lshl_add_u64 v[32:33], v[2:3], 0, s[12:13]
	s_lshl_b64 s[12:13], s[22:23], 12
	s_add_u32 s12, s11, s12
	s_addc_u32 s13, s14, s13
	s_add_i32 s24, s4, -12
	s_ashr_i32 s25, s24, 31
	s_waitcnt vmcnt(25)
	v_lshl_add_u64 v[34:35], s[12:13], 0, v[0:1]
	s_lshl_b64 s[12:13], s[24:25], 2
	s_add_u32 s12, s2, s12
	s_addc_u32 s13, s3, s13
	s_waitcnt vmcnt(17)
	v_pk_add_f32 v[10:11], v[18:19], 1.0 op_sel_hi:[1,0]
	s_nop 0
	v_pk_mul_f32 v[4:5], v[10:11], v[6:7]
	s_waitcnt vmcnt(16)
	v_pk_fma_f32 v[6:7], v[14:15], v[10:11], v[22:23]
	v_pk_add_f32 v[18:19], v[20:21], 1.0 op_sel_hi:[1,0]
	s_waitcnt vmcnt(15)
	v_pk_mul_f32 v[14:15], v[30:31], s[10:11] op_sel_hi:[1,0]
	s_nop 0
	v_fma_f32 v13, -v14, v14, v15
	v_max_f32_e32 v13, 0, v13
	v_add_f32_e32 v13, 0x3727c5ac, v13
	v_mul_f32_e32 v15, 0x4b800000, v13
	v_cmp_gt_f32_e32 vcc, s17, v13
	v_pk_fma_f32 v[10:11], v[16:17], v[18:19], v[24:25]
	v_pk_mul_f32 v[8:9], v[18:19], v[8:9]
	v_cndmask_b32_e32 v13, v13, v15, vcc
	v_rsq_f32_e32 v13, v13
	s_nop 0
	v_mul_f32_e32 v15, 0x45800000, v13
	v_cndmask_b32_e32 v16, v13, v15, vcc
	v_mul_f32_e64 v14, v16, -v14
	s_waitcnt vmcnt(14)
	v_pk_fma_f32 v[18:19], v[26:27], v[16:17], v[14:15] op_sel_hi:[1,0,0]
	v_pk_fma_f32 v[14:15], v[28:29], v[16:17], v[14:15] op_sel_hi:[1,0,0]
	v_pk_fma_f32 v[16:17], v[18:19], v[4:5], v[6:7]
	v_pk_fma_f32 v[14:15], v[14:15], v[8:9], v[10:11]
	v_cvt_pk_bf16_f32 v16, v16, v17
	v_cvt_pk_bf16_f32 v17, v14, v15
	global_store_dwordx2 v[32:33], v[16:17], off
	s_waitcnt vmcnt(13)
	v_mov_b64_e32 v[18:19], v[36:37]
	s_nop 0
	v_mov_b64_e32 v[14:15], v[52:53]
	v_mov_b64_e32 v[16:17], v[54:55]
	s_lshl_b64 s[12:13], s[22:23], 11
	s_add_i32 s22, s6, -5
	s_ashr_i32 s23, s22, 31
	v_lshl_add_u64 v[20:21], v[2:3], 0, s[12:13]
	s_lshl_b64 s[12:13], s[22:23], 12
	s_add_u32 s12, s11, s12
	s_addc_u32 s13, s14, s13
	s_add_i32 s24, s4, -10
	s_ashr_i32 s25, s24, 31
	v_lshl_add_u64 v[22:23], s[12:13], 0, v[0:1]
	s_lshl_b64 s[12:13], s[24:25], 2
	s_add_u32 s12, s2, s12
	s_addc_u32 s13, s3, s13
	v_pk_mul_f32 v[18:19], v[18:19], s[10:11] op_sel_hi:[1,0]
	s_nop 0
	v_fma_f32 v13, -v18, v18, v19
	v_max_f32_e32 v13, 0, v13
	v_add_f32_e32 v13, 0x3727c5ac, v13
	v_mul_f32_e32 v19, 0x4b800000, v13
	v_cmp_gt_f32_e32 vcc, s17, v13
	s_nop 1
	v_cndmask_b32_e32 v13, v13, v19, vcc
	v_rsq_f32_e32 v13, v13
	s_nop 0
	v_mul_f32_e32 v19, 0x45800000, v13
	v_cndmask_b32_e32 v24, v13, v19, vcc
	v_mul_f32_e64 v18, v24, -v18
	v_pk_fma_f32 v[14:15], v[14:15], v[24:25], v[18:19] op_sel_hi:[1,0,0]
	v_pk_fma_f32 v[16:17], v[16:17], v[24:25], v[18:19] op_sel_hi:[1,0,0]
	v_pk_fma_f32 v[14:15], v[14:15], v[4:5], v[6:7]
	v_pk_fma_f32 v[16:17], v[16:17], v[8:9], v[10:11]
	v_cvt_pk_bf16_f32 v14, v14, v15
	v_cvt_pk_bf16_f32 v15, v16, v17
	global_store_dwordx2 v[20:21], v[14:15], off
	s_waitcnt vmcnt(12)
	v_mov_b64_e32 v[18:19], v[38:39]
	s_nop 0
	v_mov_b64_e32 v[14:15], v[56:57]
	v_mov_b64_e32 v[16:17], v[58:59]
	s_lshl_b64 s[12:13], s[22:23], 11
	s_add_i32 s22, s6, -4
	s_ashr_i32 s23, s22, 31
	v_lshl_add_u64 v[20:21], v[2:3], 0, s[12:13]
	s_lshl_b64 s[12:13], s[22:23], 12
	s_add_u32 s12, s11, s12
	s_addc_u32 s13, s14, s13
	s_add_i32 s24, s4, -8
	s_ashr_i32 s25, s24, 31
	v_lshl_add_u64 v[22:23], s[12:13], 0, v[0:1]
	s_lshl_b64 s[12:13], s[24:25], 2
	s_add_u32 s12, s2, s12
	s_addc_u32 s13, s3, s13
	v_pk_mul_f32 v[18:19], v[18:19], s[10:11] op_sel_hi:[1,0]
	s_nop 0
	v_fma_f32 v13, -v18, v18, v19
	v_max_f32_e32 v13, 0, v13
	v_add_f32_e32 v13, 0x3727c5ac, v13
	v_mul_f32_e32 v19, 0x4b800000, v13
	v_cmp_gt_f32_e32 vcc, s17, v13
	s_nop 1
	v_cndmask_b32_e32 v13, v13, v19, vcc
	v_rsq_f32_e32 v13, v13
	s_nop 0
	v_mul_f32_e32 v19, 0x45800000, v13
	v_cndmask_b32_e32 v24, v13, v19, vcc
	v_mul_f32_e64 v18, v24, -v18
	v_pk_fma_f32 v[14:15], v[14:15], v[24:25], v[18:19] op_sel_hi:[1,0,0]
	v_pk_fma_f32 v[16:17], v[16:17], v[24:25], v[18:19] op_sel_hi:[1,0,0]
	v_pk_fma_f32 v[14:15], v[14:15], v[4:5], v[6:7]
	v_pk_fma_f32 v[16:17], v[16:17], v[8:9], v[10:11]
	v_cvt_pk_bf16_f32 v14, v14, v15
	v_cvt_pk_bf16_f32 v15, v16, v17
	global_store_dwordx2 v[20:21], v[14:15], off
	s_waitcnt vmcnt(11)
	v_mov_b64_e32 v[18:19], v[40:41]
	s_nop 0
	v_mov_b64_e32 v[14:15], v[60:61]
	v_mov_b64_e32 v[16:17], v[62:63]
	s_lshl_b64 s[12:13], s[22:23], 11
	s_add_i32 s22, s6, -3
	s_ashr_i32 s23, s22, 31
	v_lshl_add_u64 v[20:21], v[2:3], 0, s[12:13]
	s_lshl_b64 s[12:13], s[22:23], 12
	s_add_u32 s12, s11, s12
	s_addc_u32 s13, s14, s13
	s_add_i32 s24, s4, -6
	s_ashr_i32 s25, s24, 31
	v_lshl_add_u64 v[22:23], s[12:13], 0, v[0:1]
	s_lshl_b64 s[12:13], s[24:25], 2
	s_add_u32 s12, s2, s12
	s_addc_u32 s13, s3, s13
	v_pk_mul_f32 v[18:19], v[18:19], s[10:11] op_sel_hi:[1,0]
	s_nop 0
	v_fma_f32 v13, -v18, v18, v19
	v_max_f32_e32 v13, 0, v13
	v_add_f32_e32 v13, 0x3727c5ac, v13
	v_mul_f32_e32 v19, 0x4b800000, v13
	v_cmp_gt_f32_e32 vcc, s17, v13
	s_nop 1
	v_cndmask_b32_e32 v13, v13, v19, vcc
	v_rsq_f32_e32 v13, v13
	s_nop 0
	v_mul_f32_e32 v19, 0x45800000, v13
	v_cndmask_b32_e32 v24, v13, v19, vcc
	v_mul_f32_e64 v18, v24, -v18
	v_pk_fma_f32 v[14:15], v[14:15], v[24:25], v[18:19] op_sel_hi:[1,0,0]
	v_pk_fma_f32 v[16:17], v[16:17], v[24:25], v[18:19] op_sel_hi:[1,0,0]
	v_pk_fma_f32 v[14:15], v[14:15], v[4:5], v[6:7]
	v_pk_fma_f32 v[16:17], v[16:17], v[8:9], v[10:11]
	v_cvt_pk_bf16_f32 v14, v14, v15
	v_cvt_pk_bf16_f32 v15, v16, v17
	global_store_dwordx2 v[20:21], v[14:15], off
	s_waitcnt vmcnt(10)
	v_mov_b64_e32 v[18:19], v[42:43]
	s_nop 0
	v_mov_b64_e32 v[14:15], v[64:65]
	v_mov_b64_e32 v[16:17], v[66:67]
	s_lshl_b64 s[12:13], s[22:23], 11
	s_add_i32 s22, s6, -2
	s_ashr_i32 s23, s22, 31
	v_lshl_add_u64 v[20:21], v[2:3], 0, s[12:13]
	s_lshl_b64 s[12:13], s[22:23], 12
	s_add_u32 s12, s11, s12
	s_addc_u32 s13, s14, s13
	s_add_i32 s24, s4, -4
	s_ashr_i32 s25, s24, 31
	s_lshl_b64 s[24:25], s[24:25], 2
	s_add_u32 s24, s2, s24
	s_addc_u32 s25, s3, s25
	v_pk_mul_f32 v[18:19], v[18:19], s[10:11] op_sel_hi:[1,0]
	s_nop 0
	v_fma_f32 v13, -v18, v18, v19
	v_max_f32_e32 v13, 0, v13
	v_add_f32_e32 v13, 0x3727c5ac, v13
	v_mul_f32_e32 v19, 0x4b800000, v13
	v_cmp_gt_f32_e32 vcc, s17, v13
	s_nop 1
	v_cndmask_b32_e32 v13, v13, v19, vcc
	v_rsq_f32_e32 v13, v13
	s_nop 0
	v_mul_f32_e32 v19, 0x45800000, v13
	v_cndmask_b32_e32 v22, v13, v19, vcc
	v_mul_f32_e64 v18, v22, -v18
	v_pk_fma_f32 v[14:15], v[14:15], v[22:23], v[18:19] op_sel_hi:[1,0,0]
	v_pk_fma_f32 v[16:17], v[16:17], v[22:23], v[18:19] op_sel_hi:[1,0,0]
	v_pk_fma_f32 v[14:15], v[14:15], v[4:5], v[6:7]
	v_pk_fma_f32 v[16:17], v[16:17], v[8:9], v[10:11]
	v_cvt_pk_bf16_f32 v14, v14, v15
	v_cvt_pk_bf16_f32 v15, v16, v17
	global_store_dwordx2 v[20:21], v[14:15], off
	s_waitcnt vmcnt(9)
	v_mov_b64_e32 v[18:19], v[44:45]
	v_lshl_add_u64 v[14:15], s[12:13], 0, v[0:1]
	v_mov_b64_e32 v[14:15], v[68:69]
	v_mov_b64_e32 v[16:17], v[70:71]
	s_lshl_b64 s[12:13], s[22:23], 11
	s_add_i32 s22, s6, -1
	s_ashr_i32 s23, s22, 31
	v_lshl_add_u64 v[20:21], v[2:3], 0, s[12:13]
	s_lshl_b64 s[12:13], s[22:23], 12
	s_add_u32 s12, s11, s12
	s_addc_u32 s13, s14, s13
	s_add_i32 s24, s4, -2
	s_ashr_i32 s25, s24, 31
	s_lshl_b64 s[24:25], s[24:25], 2
	s_add_u32 s24, s2, s24
	s_addc_u32 s25, s3, s25
	s_ashr_i32 s5, s4, 31
	s_ashr_i32 s7, s6, 31
	v_pk_mul_f32 v[18:19], v[18:19], s[10:11] op_sel_hi:[1,0]
	s_nop 0
	v_fma_f32 v13, -v18, v18, v19
	v_max_f32_e32 v13, 0, v13
	v_add_f32_e32 v13, 0x3727c5ac, v13
	v_mul_f32_e32 v19, 0x4b800000, v13
	v_cmp_gt_f32_e32 vcc, s17, v13
	s_nop 1
	v_cndmask_b32_e32 v13, v13, v19, vcc
	v_rsq_f32_e32 v13, v13
	s_nop 0
	v_mul_f32_e32 v19, 0x45800000, v13
	v_cndmask_b32_e32 v22, v13, v19, vcc
	v_mul_f32_e64 v18, v22, -v18
	v_pk_fma_f32 v[14:15], v[14:15], v[22:23], v[18:19] op_sel_hi:[1,0,0]
	v_pk_fma_f32 v[16:17], v[16:17], v[22:23], v[18:19] op_sel_hi:[1,0,0]
	v_pk_fma_f32 v[14:15], v[14:15], v[4:5], v[6:7]
	v_pk_fma_f32 v[16:17], v[16:17], v[8:9], v[10:11]
	v_cvt_pk_bf16_f32 v14, v14, v15
	v_cvt_pk_bf16_f32 v15, v16, v17
	global_store_dwordx2 v[20:21], v[14:15], off
	s_waitcnt vmcnt(8)
	v_mov_b64_e32 v[18:19], v[46:47]
	v_lshl_add_u64 v[14:15], s[12:13], 0, v[0:1]
	v_mov_b64_e32 v[14:15], v[72:73]
	v_mov_b64_e32 v[16:17], v[74:75]
	s_lshl_b64 s[12:13], s[22:23], 11
	v_lshl_add_u64 v[20:21], v[2:3], 0, s[12:13]
	s_lshl_b64 s[12:13], s[4:5], 2
	s_add_u32 s12, s2, s12
	s_addc_u32 s13, s3, s13
	v_pk_mul_f32 v[18:19], v[18:19], s[10:11] op_sel_hi:[1,0]
	s_nop 0
	v_fma_f32 v13, -v18, v18, v19
	v_max_f32_e32 v13, 0, v13
	v_add_f32_e32 v13, 0x3727c5ac, v13
	v_mul_f32_e32 v19, 0x4b800000, v13
	v_cmp_gt_f32_e32 vcc, s17, v13
	s_nop 1
	v_cndmask_b32_e32 v13, v13, v19, vcc
	v_rsq_f32_e32 v13, v13
	s_nop 0
	v_mul_f32_e32 v19, 0x45800000, v13
	v_cndmask_b32_e32 v22, v13, v19, vcc
	v_mul_f32_e64 v18, v22, -v18
	v_pk_fma_f32 v[14:15], v[14:15], v[22:23], v[18:19] op_sel_hi:[1,0,0]
	v_pk_fma_f32 v[16:17], v[16:17], v[22:23], v[18:19] op_sel_hi:[1,0,0]
	v_pk_fma_f32 v[14:15], v[14:15], v[4:5], v[6:7]
	v_pk_fma_f32 v[16:17], v[16:17], v[8:9], v[10:11]
	v_cvt_pk_bf16_f32 v14, v14, v15
	v_cvt_pk_bf16_f32 v15, v16, v17
	global_store_dwordx2 v[20:21], v[14:15], off
	s_waitcnt vmcnt(7)
	v_mov_b64_e32 v[18:19], v[48:49]
	s_lshl_b64 s[12:13], s[6:7], 12
	s_add_u32 s12, s11, s12
	s_addc_u32 s13, s14, s13
	v_lshl_add_u64 v[0:1], s[12:13], 0, v[0:1]
	v_mov_b64_e32 v[14:15], v[76:77]
	v_mov_b64_e32 v[16:17], v[78:79]
	s_lshl_b64 s[12:13], s[6:7], 11
	v_lshl_add_u64 v[0:1], v[2:3], 0, s[12:13]
	s_add_i32 s20, s20, s101
	s_add_i32 s4, s4, s15
	s_add_i32 s6, s6, s16
	s_cmp_gt_i32 s20, s99
	v_pk_mul_f32 v[2:3], v[18:19], s[10:11] op_sel_hi:[1,0]
	s_nop 0
	v_fma_f32 v3, -v2, v2, v3
	v_max_f32_e32 v3, 0, v3
	v_add_f32_e32 v3, 0x3727c5ac, v3
	v_mul_f32_e32 v13, 0x4b800000, v3
	v_cmp_gt_f32_e32 vcc, s17, v3
	s_nop 1
	v_cndmask_b32_e32 v3, v3, v13, vcc
	v_rsq_f32_e32 v3, v3
	s_nop 0
	v_mul_f32_e32 v13, 0x45800000, v3
	v_cndmask_b32_e32 v18, v3, v13, vcc
	v_mul_f32_e64 v2, v18, -v2
	v_pk_fma_f32 v[14:15], v[14:15], v[18:19], v[2:3] op_sel_hi:[1,0,0]
	v_pk_fma_f32 v[2:3], v[16:17], v[18:19], v[2:3] op_sel_hi:[1,0,0]
	v_pk_fma_f32 v[4:5], v[14:15], v[4:5], v[6:7]
	v_pk_fma_f32 v[2:3], v[2:3], v[8:9], v[10:11]
	v_cvt_pk_bf16_f32 v4, v4, v5
	v_cvt_pk_bf16_f32 v5, v2, v3
	global_store_dwordx2 v[0:1], v[4:5], off
	s_cbranch_scc0 .LBB0_1881

.LBB0_2065:
	v_lshl_add_u64 v[30:31], v[12:13], 0, s[20:21]
	v_add_co_u32_e32 v28, vcc, 0x3c000, v30
	s_nop 1
	v_addc_co_u32_e32 v29, vcc, 0, v31, vcc
	global_load_dwordx2 v[42:43], v[28:29], off
	v_lshl_add_u64 v[28:29], v[10:11], 0, v[8:9]
	s_waitcnt lgkmcnt(0)
	global_load_dwordx4 v[38:41], v[28:29], off
	v_lshl_add_u64 v[200:201], v[24:25], 0, s[20:21]
	v_add_co_u32_e32 v200, vcc, 0x3c000, v200
	s_nop 1
	v_addc_co_u32_e32 v201, vcc, 0, v201, vcc
	global_load_dwordx2 v[202:203], v[200:201], off
	v_add_co_u32_e32 v200, vcc, s54, v28
	s_nop 1
	v_addc_co_u32_e32 v201, vcc, 0, v29, vcc
	global_load_dwordx4 v[208:211], v[200:201], off
	v_lshl_add_u64 v[200:201], v[20:21], 0, s[20:21]
	v_add_co_u32_e32 v200, vcc, 0x3c000, v200
	s_nop 1
	v_addc_co_u32_e32 v201, vcc, 0, v201, vcc
	global_load_dwordx2 v[204:205], v[200:201], off
	v_add_co_u32_e32 v200, vcc, s55, v28
	s_nop 1
	v_addc_co_u32_e32 v201, vcc, 0, v29, vcc
	global_load_dwordx4 v[212:215], v[200:201], off
	v_lshl_add_u64 v[200:201], v[16:17], 0, s[20:21]
	v_add_co_u32_e32 v200, vcc, 0x3c000, v200
	s_nop 1
	v_addc_co_u32_e32 v201, vcc, 0, v201, vcc
	global_load_dwordx2 v[206:207], v[200:201], off
	v_add_co_u32_e32 v200, vcc, s56, v28
	s_nop 1
	v_addc_co_u32_e32 v201, vcc, 0, v29, vcc
	global_load_dwordx4 v[216:219], v[200:201], off
	s_waitcnt vmcnt(7)
	v_pk_mul_f32 v[46:47], v[42:43], s[14:15] op_sel:[1,0] op_sel_hi:[0,0]
	v_fma_f32 v42, -v47, v47, v46
	v_max_f32_e32 v42, 0, v42
	v_add_f32_e32 v42, 0x3727c5ac, v42
	v_mul_f32_e32 v43, 0x4b800000, v42
	v_cmp_gt_f32_e32 vcc, s53, v42
	s_waitcnt vmcnt(6)
	v_pk_add_f32 v[38:39], v[38:39], v[46:47] op_sel:[0,1] neg_lo:[0,1] neg_hi:[0,1]
	v_pk_add_f32 v[40:41], v[40:41], v[46:47] op_sel:[0,1] neg_lo:[0,1] neg_hi:[0,1]
	v_cndmask_b32_e32 v42, v42, v43, vcc
	v_rsq_f32_e32 v48, v42
	ds_read_b128 v[42:45], v37
	v_mul_f32_e32 v46, 0x45800000, v48
	v_cndmask_b32_e32 v46, v48, v46, vcc
	v_pk_mul_f32 v[38:39], v[38:39], v[46:47] op_sel_hi:[1,0]
	v_pk_mul_f32 v[40:41], v[40:41], v[46:47] op_sel_hi:[1,0]
	v_pk_fma_f32 v[38:39], v[0:1], v[38:39], v[4:5]
	v_pk_fma_f32 v[40:41], v[2:3], v[40:41], v[6:7]
	s_waitcnt lgkmcnt(0)
	v_pk_fma_f32 v[42:43], v[38:39], s[16:17], v[42:43] op_sel_hi:[1,0,1]
	v_pk_fma_f32 v[44:45], v[40:41], s[16:17], v[44:45] op_sel_hi:[1,0,1]
	v_pk_mul_f32 v[38:39], v[42:43], v[42:43]
	v_add_f32_e32 v46, v43, v42
	v_pk_mul_f32 v[40:41], v[44:45], v[44:45]
	v_add_f32_e32 v38, v39, v38
	v_add_f32_e32 v46, v44, v46
	v_add_f32_e32 v38, v40, v38
	v_add_f32_e32 v39, v45, v46
	v_add_f32_e32 v38, v41, v38
	v_lshl_add_u64 v[46:47], v[26:27], 0, v[8:9]
	global_store_dwordx4 v[46:47], v[42:45], off offset:-8
	s_nop 1
	v_add_f32_dpp v39, v39, v39 quad_perm:[1,0,3,2] row_mask:0xf bank_mask:0xf
	v_add_f32_dpp v38, v38, v38 quad_perm:[1,0,3,2] row_mask:0xf bank_mask:0xf
	s_nop 1
	v_add_f32_dpp v39, v39, v39 quad_perm:[2,3,0,1] row_mask:0xf bank_mask:0xf
	v_add_f32_dpp v38, v38, v38 quad_perm:[2,3,0,1] row_mask:0xf bank_mask:0xf
	s_nop 1
	v_add_f32_dpp v39, v39, v39 row_half_mirror row_mask:0xf bank_mask:0xf
	v_add_f32_dpp v40, v38, v38 row_half_mirror row_mask:0xf bank_mask:0xf
	s_nop 1
	v_add_f32_dpp v38, v39, v39 row_mirror row_mask:0xf bank_mask:0xf
	v_add_f32_dpp v39, v40, v40 row_mirror row_mask:0xf bank_mask:0xf
	ds_bpermute_b32 v40, v36, v38
	ds_bpermute_b32 v41, v36, v39
	s_and_saveexec_b64 s[22:23], s[0:1]
	s_cbranch_execz .LBB0_2067
	v_add_co_u32_e32 v30, vcc, 0x4c000, v30
	s_waitcnt lgkmcnt(1)
	v_add_f32_e32 v38, v38, v40
	v_addc_co_u32_e32 v31, vcc, 0, v31, vcc
	s_waitcnt lgkmcnt(0)
	v_add_f32_e32 v39, v39, v41
	v_mov_b32_e32 v92, v30
	v_mov_b32_e32 v93, v31
	v_and_b32_e32 v90, 0x3ff, v30
	v_add_u32_e32 v90, 68608, v90
	ds_write2_b32 v90, v38, v39 offset1:1
.LBB0_2067:
	s_or_b64 exec, exec, s[22:23]
	v_lshl_add_u64 v[30:31], v[24:25], 0, s[20:21]
	v_add_co_u32_e32 v38, vcc, 0x3c000, v30
	s_nop 1
	v_addc_co_u32_e32 v39, vcc, 0, v31, vcc
	s_waitcnt vmcnt(5)
	v_mov_b64_e32 v[42:43], v[202:203]
	v_add_co_u32_e32 v38, vcc, s54, v28
	v_pk_mul_f32 v[46:47], v[42:43], s[14:15] op_sel:[1,0] op_sel_hi:[0,0]
	v_addc_co_u32_e32 v39, vcc, 0, v29, vcc
	s_waitcnt lgkmcnt(0)
	v_mov_b64_e32 v[38:39], v[208:209]
	v_mov_b64_e32 v[40:41], v[210:211]
	v_fma_f32 v42, -v47, v47, v46
	v_max_f32_e32 v42, 0, v42
	v_add_f32_e32 v42, 0x3727c5ac, v42
	v_mul_f32_e32 v43, 0x4b800000, v42
	v_cmp_gt_f32_e32 vcc, s53, v42
	v_pk_add_f32 v[38:39], v[38:39], v[46:47] op_sel:[0,1] neg_lo:[0,1] neg_hi:[0,1]
	v_cndmask_b32_e32 v42, v42, v43, vcc
	v_rsq_f32_e32 v48, v42
	ds_read_b128 v[42:45], v37 offset:4224
	v_pk_add_f32 v[40:41], v[40:41], v[46:47] op_sel:[0,1] neg_lo:[0,1] neg_hi:[0,1]
	v_mul_f32_e32 v46, 0x45800000, v48
	v_cndmask_b32_e32 v46, v48, v46, vcc
	v_pk_mul_f32 v[38:39], v[38:39], v[46:47] op_sel_hi:[1,0]
	v_pk_mul_f32 v[40:41], v[40:41], v[46:47] op_sel_hi:[1,0]
	v_pk_fma_f32 v[38:39], v[0:1], v[38:39], v[4:5]
	v_pk_fma_f32 v[40:41], v[2:3], v[40:41], v[6:7]
	s_waitcnt lgkmcnt(0)
	v_pk_fma_f32 v[42:43], v[38:39], s[16:17], v[42:43] op_sel_hi:[1,0,1]
	v_pk_fma_f32 v[44:45], v[40:41], s[16:17], v[44:45] op_sel_hi:[1,0,1]
	v_pk_mul_f32 v[38:39], v[42:43], v[42:43]
	v_add_f32_e32 v46, v43, v42
	v_pk_mul_f32 v[40:41], v[44:45], v[44:45]
	v_add_f32_e32 v38, v39, v38
	v_add_f32_e32 v46, v44, v46
	v_add_f32_e32 v38, v40, v38
	v_add_f32_e32 v39, v45, v46
	v_add_f32_e32 v38, v41, v38
	v_lshl_add_u64 v[46:47], v[22:23], 0, v[8:9]
	global_store_dwordx4 v[46:47], v[42:45], off
	s_nop 1
	v_add_f32_dpp v39, v39, v39 quad_perm:[1,0,3,2] row_mask:0xf bank_mask:0xf
	v_add_f32_dpp v38, v38, v38 quad_perm:[1,0,3,2] row_mask:0xf bank_mask:0xf
	s_nop 1
	v_add_f32_dpp v39, v39, v39 quad_perm:[2,3,0,1] row_mask:0xf bank_mask:0xf
	v_add_f32_dpp v38, v38, v38 quad_perm:[2,3,0,1] row_mask:0xf bank_mask:0xf
	s_nop 1
	v_add_f32_dpp v39, v39, v39 row_half_mirror row_mask:0xf bank_mask:0xf
	v_add_f32_dpp v40, v38, v38 row_half_mirror row_mask:0xf bank_mask:0xf
	s_nop 1
	v_add_f32_dpp v38, v39, v39 row_mirror row_mask:0xf bank_mask:0xf
	v_add_f32_dpp v39, v40, v40 row_mirror row_mask:0xf bank_mask:0xf
	ds_bpermute_b32 v40, v36, v38
	ds_bpermute_b32 v41, v36, v39
	s_and_saveexec_b64 s[22:23], s[0:1]
	s_cbranch_execz .LBB0_2069
	v_add_co_u32_e32 v30, vcc, 0x4c000, v30
	s_waitcnt lgkmcnt(1)
	v_add_f32_e32 v38, v38, v40
	v_addc_co_u32_e32 v31, vcc, 0, v31, vcc
	s_waitcnt lgkmcnt(0)
	v_add_f32_e32 v39, v39, v41
	v_mov_b32_e32 v92, v30
	v_mov_b32_e32 v93, v31
	v_and_b32_e32 v90, 0x3ff, v30
	v_add_u32_e32 v90, 68608, v90
	ds_write2_b32 v90, v38, v39 offset1:1
.LBB0_2069:
	s_or_b64 exec, exec, s[22:23]
	v_lshl_add_u64 v[30:31], v[20:21], 0, s[20:21]
	v_add_co_u32_e32 v38, vcc, 0x3c000, v30
	s_nop 1
	v_addc_co_u32_e32 v39, vcc, 0, v31, vcc
	s_waitcnt vmcnt(4)
	v_mov_b64_e32 v[42:43], v[204:205]
	v_add_co_u32_e32 v38, vcc, s55, v28
	v_pk_mul_f32 v[46:47], v[42:43], s[14:15] op_sel:[1,0] op_sel_hi:[0,0]
	v_addc_co_u32_e32 v39, vcc, 0, v29, vcc
	s_waitcnt lgkmcnt(0)
	v_mov_b64_e32 v[38:39], v[212:213]
	v_mov_b64_e32 v[40:41], v[214:215]
	v_fma_f32 v42, -v47, v47, v46
	v_max_f32_e32 v42, 0, v42
	v_add_f32_e32 v42, 0x3727c5ac, v42
	v_mul_f32_e32 v43, 0x4b800000, v42
	v_cmp_gt_f32_e32 vcc, s53, v42
	v_pk_add_f32 v[38:39], v[38:39], v[46:47] op_sel:[0,1] neg_lo:[0,1] neg_hi:[0,1]
	v_cndmask_b32_e32 v42, v42, v43, vcc
	v_rsq_f32_e32 v48, v42
	ds_read_b128 v[42:45], v37 offset:8448
	v_pk_add_f32 v[40:41], v[40:41], v[46:47] op_sel:[0,1] neg_lo:[0,1] neg_hi:[0,1]
	v_mul_f32_e32 v46, 0x45800000, v48
	v_cndmask_b32_e32 v46, v48, v46, vcc
	v_pk_mul_f32 v[38:39], v[38:39], v[46:47] op_sel_hi:[1,0]
	v_pk_mul_f32 v[40:41], v[40:41], v[46:47] op_sel_hi:[1,0]
	v_pk_fma_f32 v[38:39], v[0:1], v[38:39], v[4:5]
	v_pk_fma_f32 v[40:41], v[2:3], v[40:41], v[6:7]
	s_waitcnt lgkmcnt(0)
	v_pk_fma_f32 v[42:43], v[38:39], s[16:17], v[42:43] op_sel_hi:[1,0,1]
	v_pk_fma_f32 v[44:45], v[40:41], s[16:17], v[44:45] op_sel_hi:[1,0,1]
	v_pk_mul_f32 v[38:39], v[42:43], v[42:43]
	v_add_f32_e32 v46, v43, v42
	v_pk_mul_f32 v[40:41], v[44:45], v[44:45]
	v_add_f32_e32 v38, v39, v38
	v_add_f32_e32 v46, v44, v46
	v_add_f32_e32 v38, v40, v38
	v_add_f32_e32 v39, v45, v46
	v_add_f32_e32 v38, v41, v38
	v_lshl_add_u64 v[46:47], v[18:19], 0, v[8:9]
	global_store_dwordx4 v[46:47], v[42:45], off
	s_nop 1
	v_add_f32_dpp v39, v39, v39 quad_perm:[1,0,3,2] row_mask:0xf bank_mask:0xf
	v_add_f32_dpp v38, v38, v38 quad_perm:[1,0,3,2] row_mask:0xf bank_mask:0xf
	s_nop 1
	v_add_f32_dpp v39, v39, v39 quad_perm:[2,3,0,1] row_mask:0xf bank_mask:0xf
	v_add_f32_dpp v38, v38, v38 quad_perm:[2,3,0,1] row_mask:0xf bank_mask:0xf
	s_nop 1
	v_add_f32_dpp v39, v39, v39 row_half_mirror row_mask:0xf bank_mask:0xf
	v_add_f32_dpp v40, v38, v38 row_half_mirror row_mask:0xf bank_mask:0xf
	s_nop 1
	v_add_f32_dpp v38, v39, v39 row_mirror row_mask:0xf bank_mask:0xf
	v_add_f32_dpp v39, v40, v40 row_mirror row_mask:0xf bank_mask:0xf
	ds_bpermute_b32 v40, v36, v38
	ds_bpermute_b32 v41, v36, v39
	s_and_saveexec_b64 s[22:23], s[0:1]
	s_cbranch_execz .LBB0_2071
	v_add_co_u32_e32 v30, vcc, 0x4c000, v30
	s_waitcnt lgkmcnt(1)
	v_add_f32_e32 v38, v38, v40
	v_addc_co_u32_e32 v31, vcc, 0, v31, vcc
	s_waitcnt lgkmcnt(0)
	v_add_f32_e32 v39, v39, v41
	v_mov_b32_e32 v92, v30
	v_mov_b32_e32 v93, v31
	v_and_b32_e32 v90, 0x3ff, v30
	v_add_u32_e32 v90, 68608, v90
	ds_write2_b32 v90, v38, v39 offset1:1
.LBB0_2071:
	s_or_b64 exec, exec, s[22:23]
	v_lshl_add_u64 v[30:31], v[16:17], 0, s[20:21]
	v_add_co_u32_e32 v38, vcc, 0x3c000, v30
	s_nop 1
	v_addc_co_u32_e32 v39, vcc, 0, v31, vcc
	s_waitcnt vmcnt(3)
	v_mov_b64_e32 v[42:43], v[206:207]
	v_add_co_u32_e32 v28, vcc, s56, v28
	s_nop 1
	v_addc_co_u32_e32 v29, vcc, 0, v29, vcc
	s_waitcnt lgkmcnt(0)
	v_mov_b64_e32 v[38:39], v[216:217]
	v_mov_b64_e32 v[40:41], v[218:219]
	v_pk_mul_f32 v[28:29], v[42:43], s[14:15] op_sel:[1,0] op_sel_hi:[0,0]
	v_fma_f32 v42, -v29, v29, v28
	v_max_f32_e32 v42, 0, v42
	v_add_f32_e32 v42, 0x3727c5ac, v42
	v_mul_f32_e32 v43, 0x4b800000, v42
	v_cmp_gt_f32_e32 vcc, s53, v42
	v_pk_add_f32 v[38:39], v[38:39], v[28:29] op_sel:[0,1] neg_lo:[0,1] neg_hi:[0,1]
	v_pk_add_f32 v[28:29], v[40:41], v[28:29] op_sel:[0,1] neg_lo:[0,1] neg_hi:[0,1]
	v_cndmask_b32_e32 v42, v42, v43, vcc
	v_rsq_f32_e32 v46, v42
	ds_read_b128 v[42:45], v37 offset:12672
	v_mul_f32_e32 v40, 0x45800000, v46
	v_cndmask_b32_e32 v40, v46, v40, vcc
	v_pk_mul_f32 v[38:39], v[38:39], v[40:41] op_sel_hi:[1,0]
	v_pk_mul_f32 v[28:29], v[28:29], v[40:41] op_sel_hi:[1,0]
	v_pk_fma_f32 v[38:39], v[0:1], v[38:39], v[4:5]
	v_pk_fma_f32 v[28:29], v[2:3], v[28:29], v[6:7]
	s_waitcnt lgkmcnt(0)
	v_pk_fma_f32 v[40:41], v[38:39], s[16:17], v[42:43] op_sel_hi:[1,0,1]
	v_pk_fma_f32 v[42:43], v[28:29], s[16:17], v[44:45] op_sel_hi:[1,0,1]
	v_pk_mul_f32 v[28:29], v[40:41], v[40:41]
	v_add_f32_e32 v44, v41, v40
	v_pk_mul_f32 v[38:39], v[42:43], v[42:43]
	v_add_f32_e32 v28, v29, v28
	v_add_f32_e32 v44, v42, v44
	v_add_f32_e32 v28, v38, v28
	v_add_f32_e32 v29, v43, v44
	v_add_f32_e32 v28, v39, v28
	v_lshl_add_u64 v[44:45], v[14:15], 0, v[8:9]
	global_store_dwordx4 v[44:45], v[40:43], off
	s_nop 1
	v_add_f32_dpp v29, v29, v29 quad_perm:[1,0,3,2] row_mask:0xf bank_mask:0xf
	v_add_f32_dpp v28, v28, v28 quad_perm:[1,0,3,2] row_mask:0xf bank_mask:0xf
	s_nop 1
	v_add_f32_dpp v29, v29, v29 quad_perm:[2,3,0,1] row_mask:0xf bank_mask:0xf
	v_add_f32_dpp v28, v28, v28 quad_perm:[2,3,0,1] row_mask:0xf bank_mask:0xf
	s_nop 1
	v_add_f32_dpp v29, v29, v29 row_half_mirror row_mask:0xf bank_mask:0xf
	v_add_f32_dpp v38, v28, v28 row_half_mirror row_mask:0xf bank_mask:0xf
	s_nop 1
	v_add_f32_dpp v28, v29, v29 row_mirror row_mask:0xf bank_mask:0xf
	v_add_f32_dpp v29, v38, v38 row_mirror row_mask:0xf bank_mask:0xf
	ds_bpermute_b32 v38, v36, v28
	ds_bpermute_b32 v39, v36, v29
	s_and_saveexec_b64 s[22:23], s[0:1]
	s_cbranch_execz .LBB0_2064
	s_waitcnt lgkmcnt(1)
	v_add_f32_e32 v38, v28, v38
	v_add_co_u32_e32 v28, vcc, 0x4c000, v30
	s_waitcnt lgkmcnt(0)
	v_add_f32_e32 v39, v29, v39
	v_addc_co_u32_e32 v29, vcc, 0, v31, vcc
	v_mov_b32_e32 v92, v28
	v_mov_b32_e32 v93, v29
	v_and_b32_e32 v90, 0x3ff, v28
	v_add_u32_e32 v90, 68608, v90
	ds_write2_b32 v90, v38, v39 offset1:1
	s_branch .LBB0_2064

.LBB0_3809:
	v_lshl_add_u64 v[28:29], s[30:31], 0, v[22:23]
	v_add_co_u32_e32 v26, vcc, 0x4c000, v28
	s_nop 1
	v_addc_co_u32_e32 v27, vcc, 0, v29, vcc
	global_load_dwordx2 v[40:41], v[26:27], off
	v_lshl_add_u64 v[26:27], v[8:9], 0, s[22:23]
	s_waitcnt lgkmcnt(0)
	global_load_dwordx4 v[36:39], v[26:27], off
	v_lshl_add_u64 v[200:201], s[30:31], 0, v[20:21]
	v_add_co_u32_e32 v200, vcc, 0x4c000, v200
	s_nop 1
	v_addc_co_u32_e32 v201, vcc, 0, v201, vcc
	global_load_dwordx2 v[202:203], v[200:201], off
	v_add_co_u32_e32 v200, vcc, s55, v26
	s_nop 1
	v_addc_co_u32_e32 v201, vcc, 0, v27, vcc
	global_load_dwordx4 v[208:211], v[200:201], off
	v_lshl_add_u64 v[200:201], s[30:31], 0, v[16:17]
	v_add_co_u32_e32 v200, vcc, 0x4c000, v200
	s_nop 1
	v_addc_co_u32_e32 v201, vcc, 0, v201, vcc
	global_load_dwordx2 v[204:205], v[200:201], off
	v_add_co_u32_e32 v200, vcc, s38, v26
	s_nop 1
	v_addc_co_u32_e32 v201, vcc, 0, v27, vcc
	global_load_dwordx4 v[212:215], v[200:201], off
	v_lshl_add_u64 v[200:201], s[30:31], 0, v[12:13]
	v_add_co_u32_e32 v200, vcc, 0x4c000, v200
	s_nop 1
	v_addc_co_u32_e32 v201, vcc, 0, v201, vcc
	global_load_dwordx2 v[206:207], v[200:201], off
	v_add_co_u32_e32 v200, vcc, s56, v26
	s_nop 1
	v_addc_co_u32_e32 v201, vcc, 0, v27, vcc
	global_load_dwordx4 v[216:219], v[200:201], off
	s_waitcnt vmcnt(7)
	v_pk_mul_f32 v[44:45], v[40:41], s[16:17] op_sel:[1,0] op_sel_hi:[0,0]
	v_fma_f32 v40, -v45, v45, v44
	v_max_f32_e32 v40, 0, v40
	v_add_f32_e32 v40, 0x3727c5ac, v40
	v_mul_f32_e32 v41, 0x4b800000, v40
	v_cmp_gt_f32_e32 vcc, s53, v40
	s_waitcnt vmcnt(6)
	v_pk_add_f32 v[36:37], v[36:37], v[44:45] op_sel:[0,1] neg_lo:[0,1] neg_hi:[0,1]
	v_pk_add_f32 v[38:39], v[38:39], v[44:45] op_sel:[0,1] neg_lo:[0,1] neg_hi:[0,1]
	v_cndmask_b32_e32 v40, v40, v41, vcc
	v_rsq_f32_e32 v46, v40
	ds_read_b128 v[40:43], v35
	v_mul_f32_e32 v44, 0x45800000, v46
	v_cndmask_b32_e32 v44, v46, v44, vcc
	v_pk_mul_f32 v[36:37], v[36:37], v[44:45] op_sel_hi:[1,0]
	v_pk_mul_f32 v[38:39], v[38:39], v[44:45] op_sel_hi:[1,0]
	v_pk_fma_f32 v[36:37], v[0:1], v[36:37], v[4:5]
	v_pk_fma_f32 v[38:39], v[2:3], v[38:39], v[6:7]
	s_waitcnt lgkmcnt(0)
	v_pk_fma_f32 v[40:41], v[36:37], s[18:19], v[40:41] op_sel_hi:[1,0,1]
	v_pk_fma_f32 v[42:43], v[38:39], s[18:19], v[42:43] op_sel_hi:[1,0,1]
	v_pk_mul_f32 v[36:37], v[40:41], v[40:41]
	v_add_f32_e32 v44, v41, v40
	v_pk_mul_f32 v[38:39], v[42:43], v[42:43]
	v_add_f32_e32 v36, v37, v36
	v_add_f32_e32 v44, v42, v44
	v_add_f32_e32 v36, v38, v36
	v_add_f32_e32 v37, v43, v44
	v_add_f32_e32 v36, v39, v36
	v_lshl_add_u64 v[44:45], s[30:31], 0, v[24:25]
	v_add_co_u32_e32 v44, vcc, s54, v44
	s_nop 1
	v_add_f32_dpp v37, v37, v37 quad_perm:[1,0,3,2] row_mask:0xf bank_mask:0xf
	v_add_f32_dpp v36, v36, v36 quad_perm:[1,0,3,2] row_mask:0xf bank_mask:0xf
	v_addc_co_u32_e32 v45, vcc, 0, v45, vcc
	global_store_dwordx4 v[44:45], v[40:43], off offset:3584
	s_nop 1
	v_add_f32_dpp v37, v37, v37 quad_perm:[2,3,0,1] row_mask:0xf bank_mask:0xf
	v_add_f32_dpp v36, v36, v36 quad_perm:[2,3,0,1] row_mask:0xf bank_mask:0xf
	s_nop 1
	v_add_f32_dpp v37, v37, v37 row_half_mirror row_mask:0xf bank_mask:0xf
	v_add_f32_dpp v38, v36, v36 row_half_mirror row_mask:0xf bank_mask:0xf
	s_nop 1
	v_add_f32_dpp v36, v37, v37 row_mirror row_mask:0xf bank_mask:0xf
	v_add_f32_dpp v37, v38, v38 row_mirror row_mask:0xf bank_mask:0xf
	ds_bpermute_b32 v38, v34, v36
	ds_bpermute_b32 v39, v34, v37
	s_and_saveexec_b64 s[24:25], s[0:1]
	s_cbranch_execz .LBB0_3811
	v_add_co_u32_e32 v28, vcc, 0x5c000, v28
	s_waitcnt lgkmcnt(1)
	v_add_f32_e32 v36, v36, v38
	v_addc_co_u32_e32 v29, vcc, 0, v29, vcc
	s_waitcnt lgkmcnt(0)
	v_add_f32_e32 v37, v37, v39
	v_mov_b32_e32 v92, v28
	v_mov_b32_e32 v93, v29
	v_and_b32_e32 v90, 0x3ff, v28
	v_add_u32_e32 v90, 68608, v90
	ds_write2_b32 v90, v36, v37 offset1:1
.LBB0_3811:
	s_or_b64 exec, exec, s[24:25]
	v_lshl_add_u64 v[28:29], s[30:31], 0, v[20:21]
	v_add_co_u32_e32 v36, vcc, 0x4c000, v28
	s_nop 1
	v_addc_co_u32_e32 v37, vcc, 0, v29, vcc
	s_waitcnt vmcnt(5)
	v_mov_b64_e32 v[40:41], v[202:203]
	v_add_co_u32_e32 v36, vcc, s55, v26
	v_pk_mul_f32 v[44:45], v[40:41], s[16:17] op_sel:[1,0] op_sel_hi:[0,0]
	v_addc_co_u32_e32 v37, vcc, 0, v27, vcc
	s_waitcnt lgkmcnt(0)
	v_mov_b64_e32 v[36:37], v[208:209]
	v_mov_b64_e32 v[38:39], v[210:211]
	v_fma_f32 v40, -v45, v45, v44
	v_max_f32_e32 v40, 0, v40
	v_add_f32_e32 v40, 0x3727c5ac, v40
	v_mul_f32_e32 v41, 0x4b800000, v40
	v_cmp_gt_f32_e32 vcc, s53, v40
	v_pk_add_f32 v[36:37], v[36:37], v[44:45] op_sel:[0,1] neg_lo:[0,1] neg_hi:[0,1]
	v_cndmask_b32_e32 v40, v40, v41, vcc
	v_rsq_f32_e32 v46, v40
	ds_read_b128 v[40:43], v35 offset:4224
	v_pk_add_f32 v[38:39], v[38:39], v[44:45] op_sel:[0,1] neg_lo:[0,1] neg_hi:[0,1]
	v_mul_f32_e32 v44, 0x45800000, v46
	v_cndmask_b32_e32 v44, v46, v44, vcc
	v_pk_mul_f32 v[36:37], v[36:37], v[44:45] op_sel_hi:[1,0]
	v_pk_mul_f32 v[38:39], v[38:39], v[44:45] op_sel_hi:[1,0]
	v_pk_fma_f32 v[36:37], v[0:1], v[36:37], v[4:5]
	v_pk_fma_f32 v[38:39], v[2:3], v[38:39], v[6:7]
	s_waitcnt lgkmcnt(0)
	v_pk_fma_f32 v[40:41], v[36:37], s[18:19], v[40:41] op_sel_hi:[1,0,1]
	v_pk_fma_f32 v[42:43], v[38:39], s[18:19], v[42:43] op_sel_hi:[1,0,1]
	v_pk_mul_f32 v[36:37], v[40:41], v[40:41]
	v_add_f32_e32 v44, v41, v40
	v_pk_mul_f32 v[38:39], v[42:43], v[42:43]
	v_add_f32_e32 v36, v37, v36
	v_add_f32_e32 v44, v42, v44
	v_add_f32_e32 v36, v38, v36
	v_add_f32_e32 v37, v43, v44
	v_add_f32_e32 v36, v39, v36
	v_lshl_add_u64 v[44:45], s[30:31], 0, v[18:19]
	v_add_co_u32_e32 v44, vcc, s54, v44
	s_nop 1
	v_add_f32_dpp v37, v37, v37 quad_perm:[1,0,3,2] row_mask:0xf bank_mask:0xf
	v_add_f32_dpp v36, v36, v36 quad_perm:[1,0,3,2] row_mask:0xf bank_mask:0xf
	v_addc_co_u32_e32 v45, vcc, 0, v45, vcc
	global_store_dwordx4 v[44:45], v[40:43], off offset:3584
	s_nop 1
	v_add_f32_dpp v37, v37, v37 quad_perm:[2,3,0,1] row_mask:0xf bank_mask:0xf
	v_add_f32_dpp v36, v36, v36 quad_perm:[2,3,0,1] row_mask:0xf bank_mask:0xf
	s_nop 1
	v_add_f32_dpp v37, v37, v37 row_half_mirror row_mask:0xf bank_mask:0xf
	v_add_f32_dpp v38, v36, v36 row_half_mirror row_mask:0xf bank_mask:0xf
	s_nop 1
	v_add_f32_dpp v36, v37, v37 row_mirror row_mask:0xf bank_mask:0xf
	v_add_f32_dpp v37, v38, v38 row_mirror row_mask:0xf bank_mask:0xf
	ds_bpermute_b32 v38, v34, v36
	ds_bpermute_b32 v39, v34, v37
	s_and_saveexec_b64 s[24:25], s[0:1]
	s_cbranch_execz .LBB0_3813
	v_add_co_u32_e32 v28, vcc, 0x5c000, v28
	s_waitcnt lgkmcnt(1)
	v_add_f32_e32 v36, v36, v38
	v_addc_co_u32_e32 v29, vcc, 0, v29, vcc
	s_waitcnt lgkmcnt(0)
	v_add_f32_e32 v37, v37, v39
	v_mov_b32_e32 v92, v28
	v_mov_b32_e32 v93, v29
	v_and_b32_e32 v90, 0x3ff, v28
	v_add_u32_e32 v90, 68608, v90
	ds_write2_b32 v90, v36, v37 offset1:1
.LBB0_3813:
	s_or_b64 exec, exec, s[24:25]
	v_lshl_add_u64 v[28:29], s[30:31], 0, v[16:17]
	v_add_co_u32_e32 v36, vcc, 0x4c000, v28
	s_nop 1
	v_addc_co_u32_e32 v37, vcc, 0, v29, vcc
	s_waitcnt vmcnt(4)
	v_mov_b64_e32 v[40:41], v[204:205]
	v_add_co_u32_e32 v36, vcc, s38, v26
	v_pk_mul_f32 v[44:45], v[40:41], s[16:17] op_sel:[1,0] op_sel_hi:[0,0]
	v_addc_co_u32_e32 v37, vcc, 0, v27, vcc
	s_waitcnt lgkmcnt(0)
	v_mov_b64_e32 v[36:37], v[212:213]
	v_mov_b64_e32 v[38:39], v[214:215]
	v_fma_f32 v40, -v45, v45, v44
	v_max_f32_e32 v40, 0, v40
	v_add_f32_e32 v40, 0x3727c5ac, v40
	v_mul_f32_e32 v41, 0x4b800000, v40
	v_cmp_gt_f32_e32 vcc, s53, v40
	v_pk_add_f32 v[36:37], v[36:37], v[44:45] op_sel:[0,1] neg_lo:[0,1] neg_hi:[0,1]
	v_cndmask_b32_e32 v40, v40, v41, vcc
	v_rsq_f32_e32 v46, v40
	ds_read_b128 v[40:43], v35 offset:8448
	v_pk_add_f32 v[38:39], v[38:39], v[44:45] op_sel:[0,1] neg_lo:[0,1] neg_hi:[0,1]
	v_mul_f32_e32 v44, 0x45800000, v46
	v_cndmask_b32_e32 v44, v46, v44, vcc
	v_pk_mul_f32 v[36:37], v[36:37], v[44:45] op_sel_hi:[1,0]
	v_pk_mul_f32 v[38:39], v[38:39], v[44:45] op_sel_hi:[1,0]
	v_pk_fma_f32 v[36:37], v[0:1], v[36:37], v[4:5]
	v_pk_fma_f32 v[38:39], v[2:3], v[38:39], v[6:7]
	s_waitcnt lgkmcnt(0)
	v_pk_fma_f32 v[40:41], v[36:37], s[18:19], v[40:41] op_sel_hi:[1,0,1]
	v_pk_fma_f32 v[42:43], v[38:39], s[18:19], v[42:43] op_sel_hi:[1,0,1]
	v_pk_mul_f32 v[36:37], v[40:41], v[40:41]
	v_add_f32_e32 v44, v41, v40
	v_pk_mul_f32 v[38:39], v[42:43], v[42:43]
	v_add_f32_e32 v36, v37, v36
	v_add_f32_e32 v44, v42, v44
	v_add_f32_e32 v36, v38, v36
	v_add_f32_e32 v37, v43, v44
	v_add_f32_e32 v36, v39, v36
	v_lshl_add_u64 v[44:45], s[30:31], 0, v[14:15]
	v_add_co_u32_e32 v44, vcc, s54, v44
	s_nop 1
	v_add_f32_dpp v37, v37, v37 quad_perm:[1,0,3,2] row_mask:0xf bank_mask:0xf
	v_add_f32_dpp v36, v36, v36 quad_perm:[1,0,3,2] row_mask:0xf bank_mask:0xf
	v_addc_co_u32_e32 v45, vcc, 0, v45, vcc
	global_store_dwordx4 v[44:45], v[40:43], off offset:3584
	s_nop 1
	v_add_f32_dpp v37, v37, v37 quad_perm:[2,3,0,1] row_mask:0xf bank_mask:0xf
	v_add_f32_dpp v36, v36, v36 quad_perm:[2,3,0,1] row_mask:0xf bank_mask:0xf
	s_nop 1
	v_add_f32_dpp v37, v37, v37 row_half_mirror row_mask:0xf bank_mask:0xf
	v_add_f32_dpp v38, v36, v36 row_half_mirror row_mask:0xf bank_mask:0xf
	s_nop 1
	v_add_f32_dpp v36, v37, v37 row_mirror row_mask:0xf bank_mask:0xf
	v_add_f32_dpp v37, v38, v38 row_mirror row_mask:0xf bank_mask:0xf
	ds_bpermute_b32 v38, v34, v36
	ds_bpermute_b32 v39, v34, v37
	s_and_saveexec_b64 s[24:25], s[0:1]
	s_cbranch_execz .LBB0_3815
	v_add_co_u32_e32 v28, vcc, 0x5c000, v28
	s_waitcnt lgkmcnt(1)
	v_add_f32_e32 v36, v36, v38
	v_addc_co_u32_e32 v29, vcc, 0, v29, vcc
	s_waitcnt lgkmcnt(0)
	v_add_f32_e32 v37, v37, v39
	v_mov_b32_e32 v92, v28
	v_mov_b32_e32 v93, v29
	v_and_b32_e32 v90, 0x3ff, v28
	v_add_u32_e32 v90, 68608, v90
	ds_write2_b32 v90, v36, v37 offset1:1
.LBB0_3815:
	s_or_b64 exec, exec, s[24:25]
	v_lshl_add_u64 v[28:29], s[30:31], 0, v[12:13]
	v_add_co_u32_e32 v36, vcc, 0x4c000, v28
	s_nop 1
	v_addc_co_u32_e32 v37, vcc, 0, v29, vcc
	s_waitcnt vmcnt(3)
	v_mov_b64_e32 v[40:41], v[206:207]
	v_add_co_u32_e32 v26, vcc, s56, v26
	s_nop 1
	v_addc_co_u32_e32 v27, vcc, 0, v27, vcc
	s_waitcnt lgkmcnt(0)
	v_mov_b64_e32 v[36:37], v[216:217]
	v_mov_b64_e32 v[38:39], v[218:219]
	v_pk_mul_f32 v[26:27], v[40:41], s[16:17] op_sel:[1,0] op_sel_hi:[0,0]
	v_fma_f32 v40, -v27, v27, v26
	v_max_f32_e32 v40, 0, v40
	v_add_f32_e32 v40, 0x3727c5ac, v40
	v_mul_f32_e32 v41, 0x4b800000, v40
	v_cmp_gt_f32_e32 vcc, s53, v40
	v_pk_add_f32 v[36:37], v[36:37], v[26:27] op_sel:[0,1] neg_lo:[0,1] neg_hi:[0,1]
	v_pk_add_f32 v[26:27], v[38:39], v[26:27] op_sel:[0,1] neg_lo:[0,1] neg_hi:[0,1]
	v_cndmask_b32_e32 v40, v40, v41, vcc
	v_rsq_f32_e32 v44, v40
	ds_read_b128 v[40:43], v35 offset:12672
	v_mul_f32_e32 v38, 0x45800000, v44
	v_cndmask_b32_e32 v38, v44, v38, vcc
	v_pk_mul_f32 v[36:37], v[36:37], v[38:39] op_sel_hi:[1,0]
	v_pk_mul_f32 v[26:27], v[26:27], v[38:39] op_sel_hi:[1,0]
	v_pk_fma_f32 v[36:37], v[0:1], v[36:37], v[4:5]
	v_pk_fma_f32 v[26:27], v[2:3], v[26:27], v[6:7]
	s_waitcnt lgkmcnt(0)
	v_pk_fma_f32 v[38:39], v[36:37], s[18:19], v[40:41] op_sel_hi:[1,0,1]
	v_pk_fma_f32 v[40:41], v[26:27], s[18:19], v[42:43] op_sel_hi:[1,0,1]
	v_pk_mul_f32 v[26:27], v[38:39], v[38:39]
	v_add_f32_e32 v42, v39, v38
	v_pk_mul_f32 v[36:37], v[40:41], v[40:41]
	v_add_f32_e32 v26, v27, v26
	v_add_f32_e32 v42, v40, v42
	v_add_f32_e32 v26, v36, v26
	v_add_f32_e32 v27, v41, v42
	v_add_f32_e32 v26, v37, v26
	v_lshl_add_u64 v[42:43], s[30:31], 0, v[10:11]
	v_add_co_u32_e32 v42, vcc, s54, v42
	s_nop 1
	v_add_f32_dpp v27, v27, v27 quad_perm:[1,0,3,2] row_mask:0xf bank_mask:0xf
	v_add_f32_dpp v26, v26, v26 quad_perm:[1,0,3,2] row_mask:0xf bank_mask:0xf
	v_addc_co_u32_e32 v43, vcc, 0, v43, vcc
	global_store_dwordx4 v[42:43], v[38:41], off offset:3584
	s_nop 1
	v_add_f32_dpp v27, v27, v27 quad_perm:[2,3,0,1] row_mask:0xf bank_mask:0xf
	v_add_f32_dpp v26, v26, v26 quad_perm:[2,3,0,1] row_mask:0xf bank_mask:0xf
	s_nop 1
	v_add_f32_dpp v27, v27, v27 row_half_mirror row_mask:0xf bank_mask:0xf
	v_add_f32_dpp v36, v26, v26 row_half_mirror row_mask:0xf bank_mask:0xf
	s_nop 1
	v_add_f32_dpp v26, v27, v27 row_mirror row_mask:0xf bank_mask:0xf
	v_add_f32_dpp v27, v36, v36 row_mirror row_mask:0xf bank_mask:0xf
	ds_bpermute_b32 v36, v34, v26
	ds_bpermute_b32 v37, v34, v27
	s_and_saveexec_b64 s[24:25], s[0:1]
	s_cbranch_execz .LBB0_3808
	s_waitcnt lgkmcnt(1)
	v_add_f32_e32 v36, v26, v36
	v_add_co_u32_e32 v26, vcc, 0x5c000, v28
	s_waitcnt lgkmcnt(0)
	v_add_f32_e32 v37, v27, v37
	v_addc_co_u32_e32 v27, vcc, 0, v29, vcc
	v_mov_b32_e32 v92, v26
	v_mov_b32_e32 v93, v27
	v_and_b32_e32 v90, 0x3ff, v26
	v_add_u32_e32 v90, 68608, v90
	ds_write2_b32 v90, v36, v37 offset1:1
	s_branch .LBB0_3808

.LBB0_3870:
	s_add_i32 s9, s10, 0xffffeff9
	s_lshr_b32 s9, s9, 10
	s_mulk_i32 s9, 0x1800
	s_add_i32 s16, s10, -7
	s_add_i32 s9, s9, 0x9000
	v_mov_b32_e32 v0, v234
	s_cmpk_gt_i32 s24, 0x1ff
	s_cselect_b32 s12, s9, 0x7800
	v_lshlrev_b32_e32 v2, 2, v0
	v_ashrrev_i32_e32 v3, 31, v2
	s_lshl_b64 s[26:27], s[12:13], 2
	v_lshlrev_b64 v[0:1], 2, v[2:3]
	s_add_u32 s26, s30, s26
	v_lshl_add_u64 v[4:5], s[0:1], 0, v[0:1]
	s_addc_u32 s27, s31, s27
	v_lshl_add_u64 v[10:11], s[4:5], 0, v[0:1]
	global_load_dwordx4 v[6:9], v[4:5], off
	global_load_dwordx4 v[14:17], v[10:11], off
	s_ashr_i32 s17, s16, 31
	v_lshl_add_u64 v[4:5], s[26:27], 0, v[0:1]
	s_lshl_b64 s[26:27], s[16:17], 12
	v_add_co_u32_e32 v10, vcc, s22, v4
	s_add_u32 s26, s15, s26
	s_nop 0
	v_addc_co_u32_e32 v11, vcc, 0, v5, vcc
	v_add_co_u32_e32 v4, vcc, s23, v4
	s_addc_u32 s27, s18, s27
	s_add_i32 s34, s8, -14
	v_addc_co_u32_e32 v5, vcc, 0, v5, vcc
	s_ashr_i32 s35, s34, 31
	global_load_dwordx4 v[18:21], v[10:11], off
	global_load_dwordx4 v[22:25], v[4:5], off
	v_lshl_add_u64 v[4:5], s[26:27], 0, v[0:1]
	s_lshl_b64 s[26:27], s[34:35], 2
	s_add_u32 s26, s2, s26
	s_addc_u32 s27, s3, s27
	global_load_dwordx2 v[30:31], v12, s[26:27]
	s_waitcnt lgkmcnt(0)
	global_load_dwordx4 v[26:29], v[4:5], off
	s_add_i32 s96, s8, -12
	s_ashr_i32 s97, s96, 31
	s_lshl_b64 s[96:97], s[96:97], 2
	s_add_u32 s96, s2, s96
	s_addc_u32 s97, s3, s97
	global_load_dwordx2 v[36:37], v12, s[96:97]
	s_add_i32 s96, s10, -6
	s_ashr_i32 s97, s96, 31
	s_lshl_b64 s[96:97], s[96:97], 12
	s_add_u32 s96, s15, s96
	s_addc_u32 s97, s18, s97
	v_lshl_add_u64 v[50:51], s[96:97], 0, v[0:1]
	global_load_dwordx4 v[52:55], v[50:51], off
	s_add_i32 s96, s8, -10
	s_ashr_i32 s97, s96, 31
	s_lshl_b64 s[96:97], s[96:97], 2
	s_add_u32 s96, s2, s96
	s_addc_u32 s97, s3, s97
	global_load_dwordx2 v[38:39], v12, s[96:97]
	s_add_i32 s96, s10, -5
	s_ashr_i32 s97, s96, 31
	s_lshl_b64 s[96:97], s[96:97], 12
	s_add_u32 s96, s15, s96
	s_addc_u32 s97, s18, s97
	v_lshl_add_u64 v[50:51], s[96:97], 0, v[0:1]
	global_load_dwordx4 v[56:59], v[50:51], off
	s_add_i32 s96, s8, -8
	s_ashr_i32 s97, s96, 31
	s_lshl_b64 s[96:97], s[96:97], 2
	s_add_u32 s96, s2, s96
	s_addc_u32 s97, s3, s97
	global_load_dwordx2 v[40:41], v12, s[96:97]
	s_add_i32 s96, s10, -4
	s_ashr_i32 s97, s96, 31
	s_lshl_b64 s[96:97], s[96:97], 12
	s_add_u32 s96, s15, s96
	s_addc_u32 s97, s18, s97
	v_lshl_add_u64 v[50:51], s[96:97], 0, v[0:1]
	global_load_dwordx4 v[60:63], v[50:51], off
	s_add_i32 s96, s8, -6
	s_ashr_i32 s97, s96, 31
	s_lshl_b64 s[96:97], s[96:97], 2
	s_add_u32 s96, s2, s96
	s_addc_u32 s97, s3, s97
	global_load_dwordx2 v[42:43], v12, s[96:97]
	s_add_i32 s96, s10, -3
	s_ashr_i32 s97, s96, 31
	s_lshl_b64 s[96:97], s[96:97], 12
	s_add_u32 s96, s15, s96
	s_addc_u32 s97, s18, s97
	v_lshl_add_u64 v[50:51], s[96:97], 0, v[0:1]
	global_load_dwordx4 v[64:67], v[50:51], off
	s_add_i32 s96, s8, -4
	s_ashr_i32 s97, s96, 31
	s_lshl_b64 s[96:97], s[96:97], 2
	s_add_u32 s96, s2, s96
	s_addc_u32 s97, s3, s97
	global_load_dwordx2 v[44:45], v12, s[96:97]
	s_add_i32 s96, s10, -2
	s_ashr_i32 s97, s96, 31
	s_lshl_b64 s[96:97], s[96:97], 12
	s_add_u32 s96, s15, s96
	s_addc_u32 s97, s18, s97
	v_lshl_add_u64 v[50:51], s[96:97], 0, v[0:1]
	global_load_dwordx4 v[68:71], v[50:51], off
	s_add_i32 s96, s8, -2
	s_ashr_i32 s97, s96, 31
	s_lshl_b64 s[96:97], s[96:97], 2
	s_add_u32 s96, s2, s96
	s_addc_u32 s97, s3, s97
	global_load_dwordx2 v[46:47], v12, s[96:97]
	s_add_i32 s96, s10, -1
	s_ashr_i32 s97, s96, 31
	s_lshl_b64 s[96:97], s[96:97], 12
	s_add_u32 s96, s15, s96
	s_addc_u32 s97, s18, s97
	v_lshl_add_u64 v[50:51], s[96:97], 0, v[0:1]
	global_load_dwordx4 v[72:75], v[50:51], off
	s_add_i32 s96, s8, 0
	s_ashr_i32 s97, s96, 31
	s_lshl_b64 s[96:97], s[96:97], 2
	s_add_u32 s96, s2, s96
	s_addc_u32 s97, s3, s97
	global_load_dwordx2 v[48:49], v12, s[96:97]
	s_add_i32 s96, s10, 0
	s_ashr_i32 s97, s96, 31
	s_lshl_b64 s[96:97], s[96:97], 12
	s_add_u32 s96, s15, s96
	s_addc_u32 s97, s18, s97
	v_lshl_add_u64 v[50:51], s[96:97], 0, v[0:1]
	global_load_dwordx4 v[76:79], v[50:51], off
	s_add_i32 s26, s10, -6
	v_lshl_add_u64 v[2:3], v[2:3], 1, s[6:7]
	s_lshl_b64 s[16:17], s[16:17], 11
	s_ashr_i32 s27, s26, 31
	s_waitcnt vmcnt(26)
	v_lshl_add_u64 v[32:33], v[2:3], 0, s[16:17]
	s_lshl_b64 s[16:17], s[26:27], 12
	s_add_u32 s16, s15, s16
	s_addc_u32 s17, s18, s17
	s_add_i32 s34, s8, -12
	s_ashr_i32 s35, s34, 31
	s_waitcnt vmcnt(25)
	v_lshl_add_u64 v[34:35], s[16:17], 0, v[0:1]
	s_lshl_b64 s[16:17], s[34:35], 2
	s_add_u32 s16, s2, s16
	s_addc_u32 s17, s3, s17
	s_waitcnt vmcnt(17)
	v_pk_add_f32 v[10:11], v[18:19], 1.0 op_sel_hi:[1,0]
	s_nop 0
	v_pk_mul_f32 v[4:5], v[10:11], v[6:7]
	s_waitcnt vmcnt(16)
	v_pk_fma_f32 v[6:7], v[14:15], v[10:11], v[22:23]
	v_pk_add_f32 v[18:19], v[20:21], 1.0 op_sel_hi:[1,0]
	s_waitcnt vmcnt(15)
	v_pk_mul_f32 v[14:15], v[30:31], s[14:15] op_sel_hi:[1,0]
	s_nop 0
	v_fma_f32 v13, -v14, v14, v15
	v_max_f32_e32 v13, 0, v13
	v_add_f32_e32 v13, 0x3727c5ac, v13
	v_mul_f32_e32 v15, 0x4b800000, v13
	v_cmp_gt_f32_e32 vcc, s21, v13
	v_pk_fma_f32 v[10:11], v[16:17], v[18:19], v[24:25]
	v_pk_mul_f32 v[8:9], v[18:19], v[8:9]
	v_cndmask_b32_e32 v13, v13, v15, vcc
	v_rsq_f32_e32 v13, v13
	s_nop 0
	v_mul_f32_e32 v15, 0x45800000, v13
	v_cndmask_b32_e32 v16, v13, v15, vcc
	v_mul_f32_e64 v14, v16, -v14
	s_waitcnt vmcnt(14)
	v_pk_fma_f32 v[18:19], v[26:27], v[16:17], v[14:15] op_sel_hi:[1,0,0]
	v_pk_fma_f32 v[14:15], v[28:29], v[16:17], v[14:15] op_sel_hi:[1,0,0]
	v_pk_fma_f32 v[16:17], v[18:19], v[4:5], v[6:7]
	v_pk_fma_f32 v[14:15], v[14:15], v[8:9], v[10:11]
	v_cvt_pk_bf16_f32 v16, v16, v17
	v_cvt_pk_bf16_f32 v17, v14, v15
	global_store_dwordx2 v[32:33], v[16:17], off
	s_waitcnt vmcnt(13)
	v_mov_b64_e32 v[18:19], v[36:37]
	s_nop 0
	v_mov_b64_e32 v[14:15], v[52:53]
	v_mov_b64_e32 v[16:17], v[54:55]
	s_lshl_b64 s[16:17], s[26:27], 11
	s_add_i32 s26, s10, -5
	s_ashr_i32 s27, s26, 31
	v_lshl_add_u64 v[20:21], v[2:3], 0, s[16:17]
	s_lshl_b64 s[16:17], s[26:27], 12
	s_add_u32 s16, s15, s16
	s_addc_u32 s17, s18, s17
	s_add_i32 s34, s8, -10
	s_ashr_i32 s35, s34, 31
	v_lshl_add_u64 v[22:23], s[16:17], 0, v[0:1]
	s_lshl_b64 s[16:17], s[34:35], 2
	s_add_u32 s16, s2, s16
	s_addc_u32 s17, s3, s17
	v_pk_mul_f32 v[18:19], v[18:19], s[14:15] op_sel_hi:[1,0]
	s_nop 0
	v_fma_f32 v13, -v18, v18, v19
	v_max_f32_e32 v13, 0, v13
	v_add_f32_e32 v13, 0x3727c5ac, v13
	v_mul_f32_e32 v19, 0x4b800000, v13
	v_cmp_gt_f32_e32 vcc, s21, v13
	s_nop 1
	v_cndmask_b32_e32 v13, v13, v19, vcc
	v_rsq_f32_e32 v13, v13
	s_nop 0
	v_mul_f32_e32 v19, 0x45800000, v13
	v_cndmask_b32_e32 v24, v13, v19, vcc
	v_mul_f32_e64 v18, v24, -v18
	v_pk_fma_f32 v[14:15], v[14:15], v[24:25], v[18:19] op_sel_hi:[1,0,0]
	v_pk_fma_f32 v[16:17], v[16:17], v[24:25], v[18:19] op_sel_hi:[1,0,0]
	v_pk_fma_f32 v[14:15], v[14:15], v[4:5], v[6:7]
	v_pk_fma_f32 v[16:17], v[16:17], v[8:9], v[10:11]
	v_cvt_pk_bf16_f32 v14, v14, v15
	v_cvt_pk_bf16_f32 v15, v16, v17
	global_store_dwordx2 v[20:21], v[14:15], off
	s_waitcnt vmcnt(12)
	v_mov_b64_e32 v[18:19], v[38:39]
	s_nop 0
	v_mov_b64_e32 v[14:15], v[56:57]
	v_mov_b64_e32 v[16:17], v[58:59]
	s_lshl_b64 s[16:17], s[26:27], 11
	s_add_i32 s26, s10, -4
	s_ashr_i32 s27, s26, 31
	v_lshl_add_u64 v[20:21], v[2:3], 0, s[16:17]
	s_lshl_b64 s[16:17], s[26:27], 12
	s_add_u32 s16, s15, s16
	s_addc_u32 s17, s18, s17
	s_add_i32 s34, s8, -8
	s_ashr_i32 s35, s34, 31
	v_lshl_add_u64 v[22:23], s[16:17], 0, v[0:1]
	s_lshl_b64 s[16:17], s[34:35], 2
	s_add_u32 s16, s2, s16
	s_addc_u32 s17, s3, s17
	v_pk_mul_f32 v[18:19], v[18:19], s[14:15] op_sel_hi:[1,0]
	s_nop 0
	v_fma_f32 v13, -v18, v18, v19
	v_max_f32_e32 v13, 0, v13
	v_add_f32_e32 v13, 0x3727c5ac, v13
	v_mul_f32_e32 v19, 0x4b800000, v13
	v_cmp_gt_f32_e32 vcc, s21, v13
	s_nop 1
	v_cndmask_b32_e32 v13, v13, v19, vcc
	v_rsq_f32_e32 v13, v13
	s_nop 0
	v_mul_f32_e32 v19, 0x45800000, v13
	v_cndmask_b32_e32 v24, v13, v19, vcc
	v_mul_f32_e64 v18, v24, -v18
	v_pk_fma_f32 v[14:15], v[14:15], v[24:25], v[18:19] op_sel_hi:[1,0,0]
	v_pk_fma_f32 v[16:17], v[16:17], v[24:25], v[18:19] op_sel_hi:[1,0,0]
	v_pk_fma_f32 v[14:15], v[14:15], v[4:5], v[6:7]
	v_pk_fma_f32 v[16:17], v[16:17], v[8:9], v[10:11]
	v_cvt_pk_bf16_f32 v14, v14, v15
	v_cvt_pk_bf16_f32 v15, v16, v17
	global_store_dwordx2 v[20:21], v[14:15], off
	s_waitcnt vmcnt(11)
	v_mov_b64_e32 v[18:19], v[40:41]
	s_nop 0
	v_mov_b64_e32 v[14:15], v[60:61]
	v_mov_b64_e32 v[16:17], v[62:63]
	s_lshl_b64 s[16:17], s[26:27], 11
	s_add_i32 s26, s10, -3
	s_ashr_i32 s27, s26, 31
	v_lshl_add_u64 v[20:21], v[2:3], 0, s[16:17]
	s_lshl_b64 s[16:17], s[26:27], 12
	s_add_u32 s16, s15, s16
	s_addc_u32 s17, s18, s17
	s_add_i32 s34, s8, -6
	s_ashr_i32 s35, s34, 31
	v_lshl_add_u64 v[22:23], s[16:17], 0, v[0:1]
	s_lshl_b64 s[16:17], s[34:35], 2
	s_add_u32 s16, s2, s16
	s_addc_u32 s17, s3, s17
	v_pk_mul_f32 v[18:19], v[18:19], s[14:15] op_sel_hi:[1,0]
	s_nop 0
	v_fma_f32 v13, -v18, v18, v19
	v_max_f32_e32 v13, 0, v13
	v_add_f32_e32 v13, 0x3727c5ac, v13
	v_mul_f32_e32 v19, 0x4b800000, v13
	v_cmp_gt_f32_e32 vcc, s21, v13
	s_nop 1
	v_cndmask_b32_e32 v13, v13, v19, vcc
	v_rsq_f32_e32 v13, v13
	s_nop 0
	v_mul_f32_e32 v19, 0x45800000, v13
	v_cndmask_b32_e32 v24, v13, v19, vcc
	v_mul_f32_e64 v18, v24, -v18
	v_pk_fma_f32 v[14:15], v[14:15], v[24:25], v[18:19] op_sel_hi:[1,0,0]
	v_pk_fma_f32 v[16:17], v[16:17], v[24:25], v[18:19] op_sel_hi:[1,0,0]
	v_pk_fma_f32 v[14:15], v[14:15], v[4:5], v[6:7]
	v_pk_fma_f32 v[16:17], v[16:17], v[8:9], v[10:11]
	v_cvt_pk_bf16_f32 v14, v14, v15
	v_cvt_pk_bf16_f32 v15, v16, v17
	global_store_dwordx2 v[20:21], v[14:15], off
	s_waitcnt vmcnt(10)
	v_mov_b64_e32 v[18:19], v[42:43]
	s_nop 0
	v_mov_b64_e32 v[14:15], v[64:65]
	v_mov_b64_e32 v[16:17], v[66:67]
	s_lshl_b64 s[16:17], s[26:27], 11
	s_add_i32 s26, s10, -2
	s_ashr_i32 s27, s26, 31
	v_lshl_add_u64 v[20:21], v[2:3], 0, s[16:17]
	s_lshl_b64 s[16:17], s[26:27], 12
	s_add_u32 s16, s15, s16
	s_addc_u32 s17, s18, s17
	s_add_i32 s34, s8, -4
	s_ashr_i32 s35, s34, 31
	s_lshl_b64 s[34:35], s[34:35], 2
	s_add_u32 s34, s2, s34
	s_addc_u32 s35, s3, s35
	v_pk_mul_f32 v[18:19], v[18:19], s[14:15] op_sel_hi:[1,0]
	s_nop 0
	v_fma_f32 v13, -v18, v18, v19
	v_max_f32_e32 v13, 0, v13
	v_add_f32_e32 v13, 0x3727c5ac, v13
	v_mul_f32_e32 v19, 0x4b800000, v13
	v_cmp_gt_f32_e32 vcc, s21, v13
	s_nop 1
	v_cndmask_b32_e32 v13, v13, v19, vcc
	v_rsq_f32_e32 v13, v13
	s_nop 0
	v_mul_f32_e32 v19, 0x45800000, v13
	v_cndmask_b32_e32 v22, v13, v19, vcc
	v_mul_f32_e64 v18, v22, -v18
	v_pk_fma_f32 v[14:15], v[14:15], v[22:23], v[18:19] op_sel_hi:[1,0,0]
	v_pk_fma_f32 v[16:17], v[16:17], v[22:23], v[18:19] op_sel_hi:[1,0,0]
	v_pk_fma_f32 v[14:15], v[14:15], v[4:5], v[6:7]
	v_pk_fma_f32 v[16:17], v[16:17], v[8:9], v[10:11]
	v_cvt_pk_bf16_f32 v14, v14, v15
	v_cvt_pk_bf16_f32 v15, v16, v17
	global_store_dwordx2 v[20:21], v[14:15], off
	s_waitcnt vmcnt(9)
	v_mov_b64_e32 v[18:19], v[44:45]
	v_lshl_add_u64 v[14:15], s[16:17], 0, v[0:1]
	v_mov_b64_e32 v[14:15], v[68:69]
	v_mov_b64_e32 v[16:17], v[70:71]
	s_lshl_b64 s[16:17], s[26:27], 11
	s_add_i32 s26, s10, -1
	s_ashr_i32 s27, s26, 31
	v_lshl_add_u64 v[20:21], v[2:3], 0, s[16:17]
	s_lshl_b64 s[16:17], s[26:27], 12
	s_add_u32 s16, s15, s16
	s_addc_u32 s17, s18, s17
	s_add_i32 s34, s8, -2
	s_ashr_i32 s35, s34, 31
	s_lshl_b64 s[34:35], s[34:35], 2
	s_add_u32 s34, s2, s34
	s_addc_u32 s35, s3, s35
	s_ashr_i32 s9, s8, 31
	s_ashr_i32 s11, s10, 31
	v_pk_mul_f32 v[18:19], v[18:19], s[14:15] op_sel_hi:[1,0]
	s_nop 0
	v_fma_f32 v13, -v18, v18, v19
	v_max_f32_e32 v13, 0, v13
	v_add_f32_e32 v13, 0x3727c5ac, v13
	v_mul_f32_e32 v19, 0x4b800000, v13
	v_cmp_gt_f32_e32 vcc, s21, v13
	s_nop 1
	v_cndmask_b32_e32 v13, v13, v19, vcc
	v_rsq_f32_e32 v13, v13
	s_nop 0
	v_mul_f32_e32 v19, 0x45800000, v13
	v_cndmask_b32_e32 v22, v13, v19, vcc
	v_mul_f32_e64 v18, v22, -v18
	v_pk_fma_f32 v[14:15], v[14:15], v[22:23], v[18:19] op_sel_hi:[1,0,0]
	v_pk_fma_f32 v[16:17], v[16:17], v[22:23], v[18:19] op_sel_hi:[1,0,0]
	v_pk_fma_f32 v[14:15], v[14:15], v[4:5], v[6:7]
	v_pk_fma_f32 v[16:17], v[16:17], v[8:9], v[10:11]
	v_cvt_pk_bf16_f32 v14, v14, v15
	v_cvt_pk_bf16_f32 v15, v16, v17
	global_store_dwordx2 v[20:21], v[14:15], off
	s_waitcnt vmcnt(8)
	v_mov_b64_e32 v[18:19], v[46:47]
	v_lshl_add_u64 v[14:15], s[16:17], 0, v[0:1]
	v_mov_b64_e32 v[14:15], v[72:73]
	v_mov_b64_e32 v[16:17], v[74:75]
	s_lshl_b64 s[16:17], s[26:27], 11
	v_lshl_add_u64 v[20:21], v[2:3], 0, s[16:17]
	s_lshl_b64 s[16:17], s[8:9], 2
	s_add_u32 s16, s2, s16
	s_addc_u32 s17, s3, s17
	v_pk_mul_f32 v[18:19], v[18:19], s[14:15] op_sel_hi:[1,0]
	s_nop 0
	v_fma_f32 v13, -v18, v18, v19
	v_max_f32_e32 v13, 0, v13
	v_add_f32_e32 v13, 0x3727c5ac, v13
	v_mul_f32_e32 v19, 0x4b800000, v13
	v_cmp_gt_f32_e32 vcc, s21, v13
	s_nop 1
	v_cndmask_b32_e32 v13, v13, v19, vcc
	v_rsq_f32_e32 v13, v13
	s_nop 0
	v_mul_f32_e32 v19, 0x45800000, v13
	v_cndmask_b32_e32 v22, v13, v19, vcc
	v_mul_f32_e64 v18, v22, -v18
	v_pk_fma_f32 v[14:15], v[14:15], v[22:23], v[18:19] op_sel_hi:[1,0,0]
	v_pk_fma_f32 v[16:17], v[16:17], v[22:23], v[18:19] op_sel_hi:[1,0,0]
	v_pk_fma_f32 v[14:15], v[14:15], v[4:5], v[6:7]
	v_pk_fma_f32 v[16:17], v[16:17], v[8:9], v[10:11]
	v_cvt_pk_bf16_f32 v14, v14, v15
	v_cvt_pk_bf16_f32 v15, v16, v17
	global_store_dwordx2 v[20:21], v[14:15], off
	s_waitcnt vmcnt(7)
	v_mov_b64_e32 v[18:19], v[48:49]
	s_lshl_b64 s[16:17], s[10:11], 12
	s_add_u32 s16, s15, s16
	s_addc_u32 s17, s18, s17
	v_lshl_add_u64 v[0:1], s[16:17], 0, v[0:1]
	v_mov_b64_e32 v[14:15], v[76:77]
	v_mov_b64_e32 v[16:17], v[78:79]
	s_lshl_b64 s[16:17], s[10:11], 11
	v_lshl_add_u64 v[0:1], v[2:3], 0, s[16:17]
	s_add_i32 s24, s24, s101
	s_add_i32 s8, s8, s19
	s_add_i32 s10, s10, s20
	s_cmp_gt_i32 s24, s99
	v_pk_mul_f32 v[2:3], v[18:19], s[14:15] op_sel_hi:[1,0]
	s_nop 0
	v_fma_f32 v3, -v2, v2, v3
	v_max_f32_e32 v3, 0, v3
	v_add_f32_e32 v3, 0x3727c5ac, v3
	v_mul_f32_e32 v13, 0x4b800000, v3
	v_cmp_gt_f32_e32 vcc, s21, v3
	s_nop 1
	v_cndmask_b32_e32 v3, v3, v13, vcc
	v_rsq_f32_e32 v3, v3
	s_nop 0
	v_mul_f32_e32 v13, 0x45800000, v3
	v_cndmask_b32_e32 v18, v3, v13, vcc
	v_mul_f32_e64 v2, v18, -v2
	v_pk_fma_f32 v[14:15], v[14:15], v[18:19], v[2:3] op_sel_hi:[1,0,0]
	v_pk_fma_f32 v[2:3], v[16:17], v[18:19], v[2:3] op_sel_hi:[1,0,0]
	v_pk_fma_f32 v[4:5], v[14:15], v[4:5], v[6:7]
	v_pk_fma_f32 v[2:3], v[2:3], v[8:9], v[10:11]
	v_cvt_pk_bf16_f32 v4, v4, v5
	v_cvt_pk_bf16_f32 v5, v2, v3
	global_store_dwordx2 v[0:1], v[4:5], off
	s_cbranch_scc0 .LBB0_3870

.LBB0_4054:
	v_lshl_add_u64 v[30:31], v[12:13], 0, s[24:25]
	v_add_co_u32_e32 v28, vcc, 0x5c000, v30
	s_nop 1
	v_addc_co_u32_e32 v29, vcc, 0, v31, vcc
	global_load_dwordx2 v[42:43], v[28:29], off
	v_lshl_add_u64 v[28:29], v[10:11], 0, v[8:9]
	s_waitcnt lgkmcnt(0)
	global_load_dwordx4 v[38:41], v[28:29], off
	v_lshl_add_u64 v[200:201], v[24:25], 0, s[24:25]
	v_add_co_u32_e32 v200, vcc, 0x5c000, v200
	s_nop 1
	v_addc_co_u32_e32 v201, vcc, 0, v201, vcc
	global_load_dwordx2 v[202:203], v[200:201], off
	v_add_co_u32_e32 v200, vcc, s59, v28
	s_nop 1
	v_addc_co_u32_e32 v201, vcc, 0, v29, vcc
	global_load_dwordx4 v[208:211], v[200:201], off
	v_lshl_add_u64 v[200:201], v[20:21], 0, s[24:25]
	v_add_co_u32_e32 v200, vcc, 0x5c000, v200
	s_nop 1
	v_addc_co_u32_e32 v201, vcc, 0, v201, vcc
	global_load_dwordx2 v[204:205], v[200:201], off
	v_add_co_u32_e32 v200, vcc, s60, v28
	s_nop 1
	v_addc_co_u32_e32 v201, vcc, 0, v29, vcc
	global_load_dwordx4 v[212:215], v[200:201], off
	v_lshl_add_u64 v[200:201], v[16:17], 0, s[24:25]
	v_add_co_u32_e32 v200, vcc, 0x5c000, v200
	s_nop 1
	v_addc_co_u32_e32 v201, vcc, 0, v201, vcc
	global_load_dwordx2 v[206:207], v[200:201], off
	v_add_co_u32_e32 v200, vcc, s61, v28
	s_nop 1
	v_addc_co_u32_e32 v201, vcc, 0, v29, vcc
	global_load_dwordx4 v[216:219], v[200:201], off
	s_waitcnt vmcnt(7)
	v_pk_mul_f32 v[46:47], v[42:43], s[18:19] op_sel:[1,0] op_sel_hi:[0,0]
	v_fma_f32 v42, -v47, v47, v46
	v_max_f32_e32 v42, 0, v42
	v_add_f32_e32 v42, 0x3727c5ac, v42
	v_mul_f32_e32 v43, 0x4b800000, v42
	v_cmp_gt_f32_e32 vcc, s58, v42
	s_waitcnt vmcnt(6)
	v_pk_add_f32 v[38:39], v[38:39], v[46:47] op_sel:[0,1] neg_lo:[0,1] neg_hi:[0,1]
	v_pk_add_f32 v[40:41], v[40:41], v[46:47] op_sel:[0,1] neg_lo:[0,1] neg_hi:[0,1]
	v_cndmask_b32_e32 v42, v42, v43, vcc
	v_rsq_f32_e32 v48, v42
	ds_read_b128 v[42:45], v37
	v_mul_f32_e32 v46, 0x45800000, v48
	v_cndmask_b32_e32 v46, v48, v46, vcc
	v_pk_mul_f32 v[38:39], v[38:39], v[46:47] op_sel_hi:[1,0]
	v_pk_mul_f32 v[40:41], v[40:41], v[46:47] op_sel_hi:[1,0]
	v_pk_fma_f32 v[38:39], v[0:1], v[38:39], v[4:5]
	v_pk_fma_f32 v[40:41], v[2:3], v[40:41], v[6:7]
	s_waitcnt lgkmcnt(0)
	v_pk_fma_f32 v[42:43], v[38:39], s[20:21], v[42:43] op_sel_hi:[1,0,1]
	v_pk_fma_f32 v[44:45], v[40:41], s[20:21], v[44:45] op_sel_hi:[1,0,1]
	v_pk_mul_f32 v[38:39], v[42:43], v[42:43]
	v_add_f32_e32 v46, v43, v42
	v_pk_mul_f32 v[40:41], v[44:45], v[44:45]
	v_add_f32_e32 v38, v39, v38
	v_add_f32_e32 v46, v44, v46
	v_add_f32_e32 v38, v40, v38
	v_add_f32_e32 v39, v45, v46
	v_add_f32_e32 v38, v41, v38
	v_lshl_add_u64 v[46:47], v[26:27], 0, v[8:9]
	global_store_dwordx4 v[46:47], v[42:45], off offset:-8
	s_nop 1
	v_add_f32_dpp v39, v39, v39 quad_perm:[1,0,3,2] row_mask:0xf bank_mask:0xf
	v_add_f32_dpp v38, v38, v38 quad_perm:[1,0,3,2] row_mask:0xf bank_mask:0xf
	s_nop 1
	v_add_f32_dpp v39, v39, v39 quad_perm:[2,3,0,1] row_mask:0xf bank_mask:0xf
	v_add_f32_dpp v38, v38, v38 quad_perm:[2,3,0,1] row_mask:0xf bank_mask:0xf
	s_nop 1
	v_add_f32_dpp v39, v39, v39 row_half_mirror row_mask:0xf bank_mask:0xf
	v_add_f32_dpp v40, v38, v38 row_half_mirror row_mask:0xf bank_mask:0xf
	s_nop 1
	v_add_f32_dpp v38, v39, v39 row_mirror row_mask:0xf bank_mask:0xf
	v_add_f32_dpp v39, v40, v40 row_mirror row_mask:0xf bank_mask:0xf
	ds_bpermute_b32 v40, v36, v38
	ds_bpermute_b32 v41, v36, v39
	s_and_saveexec_b64 s[26:27], s[0:1]
	s_cbranch_execz .LBB0_4056
	v_add_co_u32_e32 v30, vcc, 0x6c000, v30
	s_waitcnt lgkmcnt(1)
	v_add_f32_e32 v38, v38, v40
	v_addc_co_u32_e32 v31, vcc, 0, v31, vcc
	s_waitcnt lgkmcnt(0)
	v_add_f32_e32 v39, v39, v41
	v_mov_b32_e32 v92, v30
	v_mov_b32_e32 v93, v31
	v_and_b32_e32 v90, 0x3ff, v30
	v_add_u32_e32 v90, 68608, v90
	ds_write2_b32 v90, v38, v39 offset1:1
.LBB0_4056:
	s_or_b64 exec, exec, s[26:27]
	v_lshl_add_u64 v[30:31], v[24:25], 0, s[24:25]
	v_add_co_u32_e32 v38, vcc, 0x5c000, v30
	s_nop 1
	v_addc_co_u32_e32 v39, vcc, 0, v31, vcc
	s_waitcnt vmcnt(5)
	v_mov_b64_e32 v[42:43], v[202:203]
	v_add_co_u32_e32 v38, vcc, s59, v28
	v_pk_mul_f32 v[46:47], v[42:43], s[18:19] op_sel:[1,0] op_sel_hi:[0,0]
	v_addc_co_u32_e32 v39, vcc, 0, v29, vcc
	s_waitcnt lgkmcnt(0)
	v_mov_b64_e32 v[38:39], v[208:209]
	v_mov_b64_e32 v[40:41], v[210:211]
	v_fma_f32 v42, -v47, v47, v46
	v_max_f32_e32 v42, 0, v42
	v_add_f32_e32 v42, 0x3727c5ac, v42
	v_mul_f32_e32 v43, 0x4b800000, v42
	v_cmp_gt_f32_e32 vcc, s58, v42
	v_pk_add_f32 v[38:39], v[38:39], v[46:47] op_sel:[0,1] neg_lo:[0,1] neg_hi:[0,1]
	v_cndmask_b32_e32 v42, v42, v43, vcc
	v_rsq_f32_e32 v48, v42
	ds_read_b128 v[42:45], v37 offset:4224
	v_pk_add_f32 v[40:41], v[40:41], v[46:47] op_sel:[0,1] neg_lo:[0,1] neg_hi:[0,1]
	v_mul_f32_e32 v46, 0x45800000, v48
	v_cndmask_b32_e32 v46, v48, v46, vcc
	v_pk_mul_f32 v[38:39], v[38:39], v[46:47] op_sel_hi:[1,0]
	v_pk_mul_f32 v[40:41], v[40:41], v[46:47] op_sel_hi:[1,0]
	v_pk_fma_f32 v[38:39], v[0:1], v[38:39], v[4:5]
	v_pk_fma_f32 v[40:41], v[2:3], v[40:41], v[6:7]
	s_waitcnt lgkmcnt(0)
	v_pk_fma_f32 v[42:43], v[38:39], s[20:21], v[42:43] op_sel_hi:[1,0,1]
	v_pk_fma_f32 v[44:45], v[40:41], s[20:21], v[44:45] op_sel_hi:[1,0,1]
	v_pk_mul_f32 v[38:39], v[42:43], v[42:43]
	v_add_f32_e32 v46, v43, v42
	v_pk_mul_f32 v[40:41], v[44:45], v[44:45]
	v_add_f32_e32 v38, v39, v38
	v_add_f32_e32 v46, v44, v46
	v_add_f32_e32 v38, v40, v38
	v_add_f32_e32 v39, v45, v46
	v_add_f32_e32 v38, v41, v38
	v_lshl_add_u64 v[46:47], v[22:23], 0, v[8:9]
	global_store_dwordx4 v[46:47], v[42:45], off
	s_nop 1
	v_add_f32_dpp v39, v39, v39 quad_perm:[1,0,3,2] row_mask:0xf bank_mask:0xf
	v_add_f32_dpp v38, v38, v38 quad_perm:[1,0,3,2] row_mask:0xf bank_mask:0xf
	s_nop 1
	v_add_f32_dpp v39, v39, v39 quad_perm:[2,3,0,1] row_mask:0xf bank_mask:0xf
	v_add_f32_dpp v38, v38, v38 quad_perm:[2,3,0,1] row_mask:0xf bank_mask:0xf
	s_nop 1
	v_add_f32_dpp v39, v39, v39 row_half_mirror row_mask:0xf bank_mask:0xf
	v_add_f32_dpp v40, v38, v38 row_half_mirror row_mask:0xf bank_mask:0xf
	s_nop 1
	v_add_f32_dpp v38, v39, v39 row_mirror row_mask:0xf bank_mask:0xf
	v_add_f32_dpp v39, v40, v40 row_mirror row_mask:0xf bank_mask:0xf
	ds_bpermute_b32 v40, v36, v38
	ds_bpermute_b32 v41, v36, v39
	s_and_saveexec_b64 s[26:27], s[0:1]
	s_cbranch_execz .LBB0_4058
	v_add_co_u32_e32 v30, vcc, 0x6c000, v30
	s_waitcnt lgkmcnt(1)
	v_add_f32_e32 v38, v38, v40
	v_addc_co_u32_e32 v31, vcc, 0, v31, vcc
	s_waitcnt lgkmcnt(0)
	v_add_f32_e32 v39, v39, v41
	v_mov_b32_e32 v92, v30
	v_mov_b32_e32 v93, v31
	v_and_b32_e32 v90, 0x3ff, v30
	v_add_u32_e32 v90, 68608, v90
	ds_write2_b32 v90, v38, v39 offset1:1
.LBB0_4058:
	s_or_b64 exec, exec, s[26:27]
	v_lshl_add_u64 v[30:31], v[20:21], 0, s[24:25]
	v_add_co_u32_e32 v38, vcc, 0x5c000, v30
	s_nop 1
	v_addc_co_u32_e32 v39, vcc, 0, v31, vcc
	s_waitcnt vmcnt(4)
	v_mov_b64_e32 v[42:43], v[204:205]
	v_add_co_u32_e32 v38, vcc, s60, v28
	v_pk_mul_f32 v[46:47], v[42:43], s[18:19] op_sel:[1,0] op_sel_hi:[0,0]
	v_addc_co_u32_e32 v39, vcc, 0, v29, vcc
	s_waitcnt lgkmcnt(0)
	v_mov_b64_e32 v[38:39], v[212:213]
	v_mov_b64_e32 v[40:41], v[214:215]
	v_fma_f32 v42, -v47, v47, v46
	v_max_f32_e32 v42, 0, v42
	v_add_f32_e32 v42, 0x3727c5ac, v42
	v_mul_f32_e32 v43, 0x4b800000, v42
	v_cmp_gt_f32_e32 vcc, s58, v42
	v_pk_add_f32 v[38:39], v[38:39], v[46:47] op_sel:[0,1] neg_lo:[0,1] neg_hi:[0,1]
	v_cndmask_b32_e32 v42, v42, v43, vcc
	v_rsq_f32_e32 v48, v42
	ds_read_b128 v[42:45], v37 offset:8448
	v_pk_add_f32 v[40:41], v[40:41], v[46:47] op_sel:[0,1] neg_lo:[0,1] neg_hi:[0,1]
	v_mul_f32_e32 v46, 0x45800000, v48
	v_cndmask_b32_e32 v46, v48, v46, vcc
	v_pk_mul_f32 v[38:39], v[38:39], v[46:47] op_sel_hi:[1,0]
	v_pk_mul_f32 v[40:41], v[40:41], v[46:47] op_sel_hi:[1,0]
	v_pk_fma_f32 v[38:39], v[0:1], v[38:39], v[4:5]
	v_pk_fma_f32 v[40:41], v[2:3], v[40:41], v[6:7]
	s_waitcnt lgkmcnt(0)
	v_pk_fma_f32 v[42:43], v[38:39], s[20:21], v[42:43] op_sel_hi:[1,0,1]
	v_pk_fma_f32 v[44:45], v[40:41], s[20:21], v[44:45] op_sel_hi:[1,0,1]
	v_pk_mul_f32 v[38:39], v[42:43], v[42:43]
	v_add_f32_e32 v46, v43, v42
	v_pk_mul_f32 v[40:41], v[44:45], v[44:45]
	v_add_f32_e32 v38, v39, v38
	v_add_f32_e32 v46, v44, v46
	v_add_f32_e32 v38, v40, v38
	v_add_f32_e32 v39, v45, v46
	v_add_f32_e32 v38, v41, v38
	v_lshl_add_u64 v[46:47], v[18:19], 0, v[8:9]
	global_store_dwordx4 v[46:47], v[42:45], off
	s_nop 1
	v_add_f32_dpp v39, v39, v39 quad_perm:[1,0,3,2] row_mask:0xf bank_mask:0xf
	v_add_f32_dpp v38, v38, v38 quad_perm:[1,0,3,2] row_mask:0xf bank_mask:0xf
	s_nop 1
	v_add_f32_dpp v39, v39, v39 quad_perm:[2,3,0,1] row_mask:0xf bank_mask:0xf
	v_add_f32_dpp v38, v38, v38 quad_perm:[2,3,0,1] row_mask:0xf bank_mask:0xf
	s_nop 1
	v_add_f32_dpp v39, v39, v39 row_half_mirror row_mask:0xf bank_mask:0xf
	v_add_f32_dpp v40, v38, v38 row_half_mirror row_mask:0xf bank_mask:0xf
	s_nop 1
	v_add_f32_dpp v38, v39, v39 row_mirror row_mask:0xf bank_mask:0xf
	v_add_f32_dpp v39, v40, v40 row_mirror row_mask:0xf bank_mask:0xf
	ds_bpermute_b32 v40, v36, v38
	ds_bpermute_b32 v41, v36, v39
	s_and_saveexec_b64 s[26:27], s[0:1]
	s_cbranch_execz .LBB0_4060
	v_add_co_u32_e32 v30, vcc, 0x6c000, v30
	s_waitcnt lgkmcnt(1)
	v_add_f32_e32 v38, v38, v40
	v_addc_co_u32_e32 v31, vcc, 0, v31, vcc
	s_waitcnt lgkmcnt(0)
	v_add_f32_e32 v39, v39, v41
	v_mov_b32_e32 v92, v30
	v_mov_b32_e32 v93, v31
	v_and_b32_e32 v90, 0x3ff, v30
	v_add_u32_e32 v90, 68608, v90
	ds_write2_b32 v90, v38, v39 offset1:1
.LBB0_4060:
	s_or_b64 exec, exec, s[26:27]
	v_lshl_add_u64 v[30:31], v[16:17], 0, s[24:25]
	v_add_co_u32_e32 v38, vcc, 0x5c000, v30
	s_nop 1
	v_addc_co_u32_e32 v39, vcc, 0, v31, vcc
	s_waitcnt vmcnt(3)
	v_mov_b64_e32 v[42:43], v[206:207]
	v_add_co_u32_e32 v28, vcc, s61, v28
	s_nop 1
	v_addc_co_u32_e32 v29, vcc, 0, v29, vcc
	s_waitcnt lgkmcnt(0)
	v_mov_b64_e32 v[38:39], v[216:217]
	v_mov_b64_e32 v[40:41], v[218:219]
	v_pk_mul_f32 v[28:29], v[42:43], s[18:19] op_sel:[1,0] op_sel_hi:[0,0]
	v_fma_f32 v42, -v29, v29, v28
	v_max_f32_e32 v42, 0, v42
	v_add_f32_e32 v42, 0x3727c5ac, v42
	v_mul_f32_e32 v43, 0x4b800000, v42
	v_cmp_gt_f32_e32 vcc, s58, v42
	v_pk_add_f32 v[38:39], v[38:39], v[28:29] op_sel:[0,1] neg_lo:[0,1] neg_hi:[0,1]
	v_pk_add_f32 v[28:29], v[40:41], v[28:29] op_sel:[0,1] neg_lo:[0,1] neg_hi:[0,1]
	v_cndmask_b32_e32 v42, v42, v43, vcc
	v_rsq_f32_e32 v46, v42
	ds_read_b128 v[42:45], v37 offset:12672
	v_mul_f32_e32 v40, 0x45800000, v46
	v_cndmask_b32_e32 v40, v46, v40, vcc
	v_pk_mul_f32 v[38:39], v[38:39], v[40:41] op_sel_hi:[1,0]
	v_pk_mul_f32 v[28:29], v[28:29], v[40:41] op_sel_hi:[1,0]
	v_pk_fma_f32 v[38:39], v[0:1], v[38:39], v[4:5]
	v_pk_fma_f32 v[28:29], v[2:3], v[28:29], v[6:7]
	s_waitcnt lgkmcnt(0)
	v_pk_fma_f32 v[40:41], v[38:39], s[20:21], v[42:43] op_sel_hi:[1,0,1]
	v_pk_fma_f32 v[42:43], v[28:29], s[20:21], v[44:45] op_sel_hi:[1,0,1]
	v_pk_mul_f32 v[28:29], v[40:41], v[40:41]
	v_add_f32_e32 v44, v41, v40
	v_pk_mul_f32 v[38:39], v[42:43], v[42:43]
	v_add_f32_e32 v28, v29, v28
	v_add_f32_e32 v44, v42, v44
	v_add_f32_e32 v28, v38, v28
	v_add_f32_e32 v29, v43, v44
	v_add_f32_e32 v28, v39, v28
	v_lshl_add_u64 v[44:45], v[14:15], 0, v[8:9]
	global_store_dwordx4 v[44:45], v[40:43], off
	s_nop 1
	v_add_f32_dpp v29, v29, v29 quad_perm:[1,0,3,2] row_mask:0xf bank_mask:0xf
	v_add_f32_dpp v28, v28, v28 quad_perm:[1,0,3,2] row_mask:0xf bank_mask:0xf
	s_nop 1
	v_add_f32_dpp v29, v29, v29 quad_perm:[2,3,0,1] row_mask:0xf bank_mask:0xf
	v_add_f32_dpp v28, v28, v28 quad_perm:[2,3,0,1] row_mask:0xf bank_mask:0xf
	s_nop 1
	v_add_f32_dpp v29, v29, v29 row_half_mirror row_mask:0xf bank_mask:0xf
	v_add_f32_dpp v38, v28, v28 row_half_mirror row_mask:0xf bank_mask:0xf
	s_nop 1
	v_add_f32_dpp v28, v29, v29 row_mirror row_mask:0xf bank_mask:0xf
	v_add_f32_dpp v29, v38, v38 row_mirror row_mask:0xf bank_mask:0xf
	ds_bpermute_b32 v38, v36, v28
	ds_bpermute_b32 v39, v36, v29
	s_and_saveexec_b64 s[26:27], s[0:1]
	s_cbranch_execz .LBB0_4053
	s_waitcnt lgkmcnt(1)
	v_add_f32_e32 v38, v28, v38
	v_add_co_u32_e32 v28, vcc, 0x6c000, v30
	s_waitcnt lgkmcnt(0)
	v_add_f32_e32 v39, v29, v39
	v_addc_co_u32_e32 v29, vcc, 0, v31, vcc
	v_mov_b32_e32 v92, v28
	v_mov_b32_e32 v93, v29
	v_and_b32_e32 v90, 0x3ff, v28
	v_add_u32_e32 v90, 68608, v90
	ds_write2_b32 v90, v38, v39 offset1:1
	s_branch .LBB0_4053

.LBB0_4062:
	v_readlane_b32 s66, v251, 55
	v_readlane_b32 s67, v251, 56
	s_cmp_gt_i32 s67, 21
	s_cbranch_scc0 .LBB0_4112
	s_waitcnt vmcnt(0)
	s_waitcnt vmcnt(63) expcnt(7) lgkmcnt(15)
	s_barrier
	s_mov_b64 s[4:5], exec
	v_readlane_b32 s2, v251, 3
	v_readlane_b32 s3, v251, 4
	s_and_b64 s[2:3], s[4:5], s[2:3]
	s_mov_b64 exec, s[2:3]
	s_cbranch_execz .Lxb_done_21
	v_mov_b32_e32 v0, 0
	s_waitcnt vmcnt(0) expcnt(0) lgkmcnt(0)
	ds_read_b32 v2, v0
	ds_read_b32 v1, v0 offset:4
	v_readlane_b32 s0, v251, 2
	v_readlane_b32 s6, v251, 5
	v_readlane_b32 s7, v251, 6
	s_lshl_b32 s0, s0, 8
	s_add_u32 s8, s6, s0
	s_addc_u32 s9, s7, 0
	v_mov_b32_e32 v3, 1
	v_mov_b32_e32 v4, 0x1000
	s_nop 4
	global_atomic_add v3, v4, v3, s[8:9] offset:1024 sc0
	buffer_inv sc1
	s_sub_u32 s10, 20, s66
	s_add_u32 s11, s10, 1
	s_waitcnt lgkmcnt(0)
	v_readfirstlane_b32 s12, v2
	v_readfirstlane_b32 s13, v1
	s_mul_i32 s14, s12, s11
	s_mul_i32 s15, s13, s11
	s_waitcnt vmcnt(0)
	v_readfirstlane_b32 s16, v3
	s_add_u32 s16, s16, 1
	s_cmp_lg_u32 s16, s14
	s_cbranch_scc1 .Lxb_wait_21
	v_readlane_b32 s17, v250, 60
	s_cmp_lg_u32 s17, 0
	s_cbranch_scc1 .Lxb_glob_21
	s_waitcnt vmcnt(0)
	v_mov_b32_e32 v3, 1
	v_mov_b32_e32 v4, 0x7f000
	global_atomic_add v3, v4, v3, s[30:31] offset:1024 sc0
	s_waitcnt vmcnt(0)
	v_mov_b32_e32 v3, 1
	v_mov_b32_e32 v4, s0
	v_add_u32_e32 v4, 0x2400, v4
	global_atomic_add v4, v3, s[6:7]
	s_branch .Lxb_wait_21

.LBB0_4112:
	s_cmp_gt_i32 s66, 21
	s_cselect_b64 s[0:1], -1, 0
	s_cmp_lt_i32 s67, 22
	s_cselect_b64 s[2:3], -1, 0
	s_or_b64 s[0:1], s[0:1], s[2:3]
	s_and_b64 vcc, exec, s[0:1]
	s_cbranch_vccnz .LBB0_4166
	s_cmpk_gt_i32 s78, 0x3ff
	s_cbranch_scc1 .LBB0_4116
	s_mov_b32 s100, s78
	s_mov_b32 s101, s64
	s_movk_i32 s99, 0x3ff
	s_cmpk_eq_i32 s64, 0x200
	s_cbranch_scc0 .Lfm_nomap
	s_and_b32 s99, s78, 7
	s_lshl_b32 s99, s99, 7
	s_lshr_b32 s100, s78, 3
	s_add_i32 s100, s100, s99
	s_add_i32 s99, s99, 0x7f
	s_movk_i32 s101, 64
.Lfm_nomap:
	v_readlane_b32 s4, v250, 6
	s_add_u32 s2, s30, 0x6c000
	v_readlane_b32 s12, v250, 14
	v_readlane_b32 s13, v250, 15
	v_readlane_b32 s14, v250, 16
	v_readlane_b32 s15, v250, 17
	v_readlane_b32 s16, v250, 18
	v_readlane_b32 s17, v250, 19
	s_addc_u32 s3, s31, 0
	v_readlane_b32 s18, v250, 20
	v_readlane_b32 s19, v250, 21
	s_mov_b64 s[12:13], s[16:17]
	s_add_u32 s0, s12, 0x1000
	s_mov_b64 s[14:15], s[18:19]
	s_addc_u32 s1, s13, 0
	v_readlane_b32 s5, v250, 7
	v_readlane_b32 s6, v250, 8
	v_readlane_b32 s7, v250, 9
	s_add_u32 s4, s14, 0x1000
	v_readlane_b32 s8, v250, 10
	v_readlane_b32 s10, v250, 12
	v_readlane_b32 s11, v250, 13
	s_addc_u32 s5, s15, 0
	s_lshl_b32 s6, s100, 3
	s_lshl_b32 s7, s100, 4
	s_or_b32 s6, s6, 7
	s_lshl_b32 s11, s101, 3
	s_or_b32 s8, s7, 14
	s_lshl_b32 s14, s101, 4
	s_waitcnt vmcnt(11)
	v_mov_b32_e32 v10, 0
	s_mov_b32 s10, 0x3a800000
	s_mov_b32 s15, 0x800000
	v_readlane_b32 s9, v250, 11
.LBB0_4115:
	s_add_i32 s16, s8, -14
	s_ashr_i32 s17, s16, 31
	s_add_i32 s12, s6, -7
	s_lshl_b64 s[16:17], s[16:17], 2
	s_add_u32 s16, s2, s16
	v_mov_b32_e32 v0, v234
	s_addc_u32 s17, s3, s17
	global_load_dwordx2 v[20:21], v10, s[16:17]
	s_ashr_i32 s13, s12, 31
	v_lshlrev_b32_e32 v0, 2, v0
	s_lshl_b64 s[12:13], s[12:13], 12
	v_ashrrev_i32_e32 v1, 31, v0
	s_add_u32 s12, s28, s12
	v_lshlrev_b64 v[8:9], 2, v[0:1]
	s_addc_u32 s13, s29, s13
	v_lshl_add_u64 v[0:1], s[0:1], 0, v[8:9]
	s_waitcnt vmcnt(9)
	v_lshl_add_u64 v[22:23], s[12:13], 0, v[8:9]
	v_lshl_add_u64 v[16:17], s[4:5], 0, v[8:9]
	global_load_dwordx4 v[0:3], v[0:1], off
	s_nop 0
	global_load_dwordx4 v[12:15], v[22:23], off
	global_load_dwordx4 v[4:7], v[16:17], off
	s_add_i32 s16, s8, -12
	s_ashr_i32 s17, s16, 31
	s_add_i32 s12, s6, -6
	s_lshl_b64 s[16:17], s[16:17], 2
	s_add_u32 s16, s2, s16
	s_addc_u32 s17, s3, s17
	s_ashr_i32 s13, s12, 31
	s_lshl_b64 s[12:13], s[12:13], 12
	s_add_u32 s12, s28, s12
	s_addc_u32 s13, s29, s13
	v_lshl_add_u64 v[24:25], s[12:13], 0, v[8:9]
	global_load_dwordx4 v[16:19], v[24:25], off
	s_add_i32 s12, s6, -5
	s_waitcnt vmcnt(4)
	v_pk_mul_f32 v[20:21], v[20:21], s[10:11] op_sel_hi:[1,0]
	s_nop 0
	v_fma_f32 v11, -v20, v20, v21
	v_max_f32_e32 v11, 0, v11
	v_add_f32_e32 v11, 0x3727c5ac, v11
	s_waitcnt lgkmcnt(1)
	v_mul_f32_e32 v26, 0x4b800000, v11
	v_cmp_gt_f32_e32 vcc, s15, v11
	s_waitcnt vmcnt(2)
	v_pk_add_f32 v[12:13], v[12:13], v[20:21] op_sel_hi:[1,0] neg_lo:[0,1] neg_hi:[0,1]
	v_cndmask_b32_e32 v11, v11, v26, vcc
	v_rsq_f32_e32 v11, v11
	v_pk_add_f32 v[14:15], v[14:15], v[20:21] op_sel_hi:[1,0] neg_lo:[0,1] neg_hi:[0,1]
	v_mul_f32_e32 v20, 0x45800000, v11
	v_cndmask_b32_e32 v20, v11, v20, vcc
	v_pk_mul_f32 v[12:13], v[12:13], v[20:21] op_sel_hi:[1,0]
	v_pk_mul_f32 v[14:15], v[14:15], v[20:21] op_sel_hi:[1,0]
	s_waitcnt vmcnt(1)
	v_pk_fma_f32 v[12:13], v[0:1], v[12:13], v[4:5]
	v_pk_fma_f32 v[14:15], v[2:3], v[14:15], v[6:7]
	global_store_dwordx4 v[22:23], v[12:15], off
	global_load_dwordx2 v[12:13], v10, s[16:17]
	s_add_i32 s16, s8, -10
	s_ashr_i32 s17, s16, 31
	s_lshl_b64 s[16:17], s[16:17], 2
	s_add_u32 s16, s2, s16
	s_addc_u32 s17, s3, s17
	s_ashr_i32 s13, s12, 31
	s_lshl_b64 s[12:13], s[12:13], 12
	s_add_u32 s12, s28, s12
	s_addc_u32 s13, s29, s13
	v_lshl_add_u64 v[20:21], s[12:13], 0, v[8:9]
	s_add_i32 s12, s6, -4
	s_waitcnt vmcnt(0)
	v_pk_mul_f32 v[12:13], v[12:13], s[10:11] op_sel_hi:[1,0]
	s_nop 0
	v_fma_f32 v11, -v12, v12, v13
	v_max_f32_e32 v11, 0, v11
	v_add_f32_e32 v11, 0x3727c5ac, v11
	v_pk_add_f32 v[14:15], v[16:17], v[12:13] op_sel_hi:[1,0] neg_lo:[0,1] neg_hi:[0,1]
	v_mul_f32_e32 v16, 0x4b800000, v11
	v_cmp_gt_f32_e32 vcc, s15, v11
	v_pk_add_f32 v[12:13], v[18:19], v[12:13] op_sel_hi:[1,0] neg_lo:[0,1] neg_hi:[0,1]
	s_nop 0
	v_cndmask_b32_e32 v11, v11, v16, vcc
	v_rsq_f32_e32 v11, v11
	s_nop 0
	v_mul_f32_e32 v16, 0x45800000, v11
	v_cndmask_b32_e32 v16, v11, v16, vcc
	v_pk_mul_f32 v[14:15], v[14:15], v[16:17] op_sel_hi:[1,0]
	v_pk_mul_f32 v[16:17], v[12:13], v[16:17] op_sel_hi:[1,0]
	v_pk_fma_f32 v[12:13], v[0:1], v[14:15], v[4:5]
	v_pk_fma_f32 v[14:15], v[2:3], v[16:17], v[6:7]
	global_store_dwordx4 v[24:25], v[12:15], off
	global_load_dwordx2 v[22:23], v10, s[16:17]
	s_nop 0
	global_load_dwordx4 v[12:15], v[20:21], off
	s_add_i32 s16, s8, -8
	s_ashr_i32 s17, s16, 31
	s_lshl_b64 s[16:17], s[16:17], 2
	s_add_u32 s16, s2, s16
	s_addc_u32 s17, s3, s17
	s_ashr_i32 s13, s12, 31
	s_lshl_b64 s[12:13], s[12:13], 12
	s_add_u32 s12, s28, s12
	s_addc_u32 s13, s29, s13
	v_lshl_add_u64 v[24:25], s[12:13], 0, v[8:9]
	global_load_dwordx4 v[16:19], v[24:25], off
	s_add_i32 s12, s6, -3
	s_waitcnt vmcnt(2)
	v_pk_mul_f32 v[22:23], v[22:23], s[10:11] op_sel_hi:[1,0]
	s_nop 0
	v_fma_f32 v11, -v22, v22, v23
	v_max_f32_e32 v11, 0, v11
	v_add_f32_e32 v11, 0x3727c5ac, v11
	s_waitcnt vmcnt(1)
	v_pk_add_f32 v[12:13], v[12:13], v[22:23] op_sel_hi:[1,0] neg_lo:[0,1] neg_hi:[0,1]
	v_pk_add_f32 v[14:15], v[14:15], v[22:23] op_sel_hi:[1,0] neg_lo:[0,1] neg_hi:[0,1]
	v_mul_f32_e32 v22, 0x4b800000, v11
	v_cmp_gt_f32_e32 vcc, s15, v11
	s_nop 1
	v_cndmask_b32_e32 v11, v11, v22, vcc
	v_rsq_f32_e32 v11, v11
	s_nop 0
	v_mul_f32_e32 v22, 0x45800000, v11
	v_cndmask_b32_e32 v22, v11, v22, vcc
	v_pk_mul_f32 v[12:13], v[12:13], v[22:23] op_sel_hi:[1,0]
	v_pk_mul_f32 v[14:15], v[14:15], v[22:23] op_sel_hi:[1,0]
	v_pk_fma_f32 v[12:13], v[0:1], v[12:13], v[4:5]
	v_pk_fma_f32 v[14:15], v[2:3], v[14:15], v[6:7]
	global_store_dwordx4 v[20:21], v[12:15], off
	global_load_dwordx2 v[12:13], v10, s[16:17]
	s_add_i32 s16, s8, -6
	s_ashr_i32 s17, s16, 31
	s_lshl_b64 s[16:17], s[16:17], 2
	s_add_u32 s16, s2, s16
	s_addc_u32 s17, s3, s17
	s_ashr_i32 s13, s12, 31
	s_lshl_b64 s[12:13], s[12:13], 12
	s_add_u32 s12, s28, s12
	s_addc_u32 s13, s29, s13
	v_lshl_add_u64 v[20:21], s[12:13], 0, v[8:9]
	s_add_i32 s12, s6, -2
	s_waitcnt vmcnt(0)
	v_pk_mul_f32 v[12:13], v[12:13], s[10:11] op_sel_hi:[1,0]
	s_nop 0
	v_fma_f32 v11, -v12, v12, v13
	v_max_f32_e32 v11, 0, v11
	v_add_f32_e32 v11, 0x3727c5ac, v11
	v_pk_add_f32 v[14:15], v[16:17], v[12:13] op_sel_hi:[1,0] neg_lo:[0,1] neg_hi:[0,1]
	v_mul_f32_e32 v16, 0x4b800000, v11
	v_cmp_gt_f32_e32 vcc, s15, v11
	v_pk_add_f32 v[12:13], v[18:19], v[12:13] op_sel_hi:[1,0] neg_lo:[0,1] neg_hi:[0,1]
	s_nop 0
	v_cndmask_b32_e32 v11, v11, v16, vcc
	v_rsq_f32_e32 v11, v11
	s_nop 0
	v_mul_f32_e32 v16, 0x45800000, v11
	v_cndmask_b32_e32 v16, v11, v16, vcc
	v_pk_mul_f32 v[14:15], v[14:15], v[16:17] op_sel_hi:[1,0]
	v_pk_mul_f32 v[16:17], v[12:13], v[16:17] op_sel_hi:[1,0]
	v_pk_fma_f32 v[12:13], v[0:1], v[14:15], v[4:5]
	v_pk_fma_f32 v[14:15], v[2:3], v[16:17], v[6:7]
	global_store_dwordx4 v[24:25], v[12:15], off
	global_load_dwordx2 v[22:23], v10, s[16:17]
	s_nop 0
	global_load_dwordx4 v[12:15], v[20:21], off
	s_add_i32 s16, s8, -4
	s_ashr_i32 s17, s16, 31
	s_lshl_b64 s[16:17], s[16:17], 2
	s_add_u32 s16, s2, s16
	s_addc_u32 s17, s3, s17
	s_ashr_i32 s13, s12, 31
	s_lshl_b64 s[12:13], s[12:13], 12
	s_add_u32 s12, s28, s12
	s_addc_u32 s13, s29, s13
	v_lshl_add_u64 v[24:25], s[12:13], 0, v[8:9]
	global_load_dwordx4 v[16:19], v[24:25], off
	s_add_i32 s12, s6, -1
	s_waitcnt vmcnt(2)
	v_pk_mul_f32 v[22:23], v[22:23], s[10:11] op_sel_hi:[1,0]
	s_nop 0
	v_fma_f32 v11, -v22, v22, v23
	v_max_f32_e32 v11, 0, v11
	v_add_f32_e32 v11, 0x3727c5ac, v11
	s_waitcnt vmcnt(1)
	v_pk_add_f32 v[12:13], v[12:13], v[22:23] op_sel_hi:[1,0] neg_lo:[0,1] neg_hi:[0,1]
	v_pk_add_f32 v[14:15], v[14:15], v[22:23] op_sel_hi:[1,0] neg_lo:[0,1] neg_hi:[0,1]
	v_mul_f32_e32 v22, 0x4b800000, v11
	v_cmp_gt_f32_e32 vcc, s15, v11
	s_nop 1
	v_cndmask_b32_e32 v11, v11, v22, vcc
	v_rsq_f32_e32 v11, v11
	s_nop 0
	v_mul_f32_e32 v22, 0x45800000, v11
	v_cndmask_b32_e32 v22, v11, v22, vcc
	v_pk_mul_f32 v[12:13], v[12:13], v[22:23] op_sel_hi:[1,0]
	v_pk_mul_f32 v[14:15], v[14:15], v[22:23] op_sel_hi:[1,0]
	v_pk_fma_f32 v[12:13], v[0:1], v[12:13], v[4:5]
	v_pk_fma_f32 v[14:15], v[2:3], v[14:15], v[6:7]
	global_store_dwordx4 v[20:21], v[12:15], off
	global_load_dwordx2 v[12:13], v10, s[16:17]
	s_add_i32 s16, s8, -2
	s_ashr_i32 s17, s16, 31
	s_lshl_b64 s[16:17], s[16:17], 2
	s_add_u32 s16, s2, s16
	s_addc_u32 s17, s3, s17
	s_ashr_i32 s13, s12, 31
	s_lshl_b64 s[12:13], s[12:13], 12
	s_add_u32 s12, s28, s12
	s_addc_u32 s13, s29, s13
	v_lshl_add_u64 v[20:21], s[12:13], 0, v[8:9]
	s_ashr_i32 s9, s8, 31
	s_lshl_b64 s[12:13], s[8:9], 2
	s_add_u32 s12, s2, s12
	s_addc_u32 s13, s3, s13
	s_ashr_i32 s7, s6, 31
	s_waitcnt vmcnt(0)
	v_pk_mul_f32 v[12:13], v[12:13], s[10:11] op_sel_hi:[1,0]
	s_nop 0
	v_fma_f32 v11, -v12, v12, v13
	v_max_f32_e32 v11, 0, v11
	v_add_f32_e32 v11, 0x3727c5ac, v11
	v_pk_add_f32 v[14:15], v[16:17], v[12:13] op_sel_hi:[1,0] neg_lo:[0,1] neg_hi:[0,1]
	v_mul_f32_e32 v16, 0x4b800000, v11
	v_cmp_gt_f32_e32 vcc, s15, v11
	v_pk_add_f32 v[12:13], v[18:19], v[12:13] op_sel_hi:[1,0] neg_lo:[0,1] neg_hi:[0,1]
	s_nop 0
	v_cndmask_b32_e32 v11, v11, v16, vcc
	v_rsq_f32_e32 v11, v11
	s_nop 0
	v_mul_f32_e32 v16, 0x45800000, v11
	v_cndmask_b32_e32 v16, v11, v16, vcc
	v_pk_mul_f32 v[14:15], v[14:15], v[16:17] op_sel_hi:[1,0]
	v_pk_mul_f32 v[16:17], v[12:13], v[16:17] op_sel_hi:[1,0]
	v_pk_fma_f32 v[12:13], v[0:1], v[14:15], v[4:5]
	v_pk_fma_f32 v[14:15], v[2:3], v[16:17], v[6:7]
	global_store_dwordx4 v[24:25], v[12:15], off
	global_load_dwordx2 v[22:23], v10, s[16:17]
	s_nop 0
	global_load_dwordx4 v[12:15], v[20:21], off
	s_lshl_b64 s[16:17], s[6:7], 12
	s_add_u32 s16, s28, s16
	s_addc_u32 s17, s29, s17
	v_lshl_add_u64 v[8:9], s[16:17], 0, v[8:9]
	global_load_dwordx4 v[16:19], v[8:9], off
	s_add_i32 s100, s100, s101
	s_add_i32 s6, s6, s11
	s_add_i32 s8, s8, s14
	s_cmp_gt_i32 s100, s99
	s_waitcnt vmcnt(2)
	v_pk_mul_f32 v[22:23], v[22:23], s[10:11] op_sel_hi:[1,0]
	s_nop 0
	v_fma_f32 v11, -v22, v22, v23
	v_max_f32_e32 v11, 0, v11
	v_add_f32_e32 v11, 0x3727c5ac, v11
	s_waitcnt vmcnt(1)
	v_pk_add_f32 v[12:13], v[12:13], v[22:23] op_sel_hi:[1,0] neg_lo:[0,1] neg_hi:[0,1]
	v_pk_add_f32 v[14:15], v[14:15], v[22:23] op_sel_hi:[1,0] neg_lo:[0,1] neg_hi:[0,1]
	v_mul_f32_e32 v22, 0x4b800000, v11
	v_cmp_gt_f32_e32 vcc, s15, v11
	s_nop 1
	v_cndmask_b32_e32 v11, v11, v22, vcc
	v_rsq_f32_e32 v11, v11
	s_nop 0
	v_mul_f32_e32 v22, 0x45800000, v11
	v_cndmask_b32_e32 v22, v11, v22, vcc
	v_pk_mul_f32 v[12:13], v[12:13], v[22:23] op_sel_hi:[1,0]
	v_pk_mul_f32 v[14:15], v[14:15], v[22:23] op_sel_hi:[1,0]
	v_pk_fma_f32 v[12:13], v[0:1], v[12:13], v[4:5]
	v_pk_fma_f32 v[14:15], v[2:3], v[14:15], v[6:7]
	global_store_dwordx4 v[20:21], v[12:15], off
	global_load_dwordx2 v[12:13], v10, s[12:13]
	s_waitcnt vmcnt(0)
	v_pk_mul_f32 v[12:13], v[12:13], s[10:11] op_sel_hi:[1,0]
	s_nop 0
	v_fma_f32 v11, -v12, v12, v13
	v_max_f32_e32 v11, 0, v11
	v_add_f32_e32 v11, 0x3727c5ac, v11
	v_pk_add_f32 v[14:15], v[16:17], v[12:13] op_sel_hi:[1,0] neg_lo:[0,1] neg_hi:[0,1]
	v_mul_f32_e32 v16, 0x4b800000, v11
	v_cmp_gt_f32_e32 vcc, s15, v11
	v_pk_add_f32 v[12:13], v[18:19], v[12:13] op_sel_hi:[1,0] neg_lo:[0,1] neg_hi:[0,1]
	s_nop 0
	v_cndmask_b32_e32 v11, v11, v16, vcc
	v_rsq_f32_e32 v11, v11
	s_nop 0
	v_mul_f32_e32 v16, 0x45800000, v11
	v_cndmask_b32_e32 v16, v11, v16, vcc
	v_pk_mul_f32 v[14:15], v[14:15], v[16:17] op_sel_hi:[1,0]
	v_pk_mul_f32 v[12:13], v[12:13], v[16:17] op_sel_hi:[1,0]
	v_pk_fma_f32 v[0:1], v[0:1], v[14:15], v[4:5]
	v_pk_fma_f32 v[2:3], v[2:3], v[12:13], v[6:7]
	global_store_dwordx4 v[8:9], v[0:3], off
	s_cbranch_scc0 .LBB0_4115
